# first K iteration peeled in all seven GEMM K-loops (C=0 on first MFMA per accumulator), accumulator zeroing removed
# speedup vs baseline: 1.0137x; 1.0024x over previous
.LBB0_68:
	v_and_b32_e32 v189, 15, v170
	v_bfe_u32 v135, v170, 4, 2
	v_lshlrev_b32_e32 v188, 6, v189
	v_lshlrev_b32_e32 v16, 2, v170
	s_and_b32 s26, s9, 3
	v_lshl_or_b32 v15, v135, 4, v188
	s_lshl_b32 s9, s10, 13
	v_and_b32_e32 v190, 32, v16
	s_add_i32 m0, s3, 0x18000
	v_lshl_add_u64 v[8:9], v[8:9], 0, s[14:15]
	v_bitop3_b32 v16, v15, s9, v190 bitop3:0xde
	s_lshl_b32 s9, s26, 12
	s_waitcnt vmcnt(2)
	s_barrier
	global_load_lds_dwordx4 v[8:9], off
	v_lshl_add_u64 v[6:7], v[6:7], 0, s[14:15]
	s_add_i32 m0, s3, 0x1a000
	s_add_i32 s36, s3, 0x8000
	s_add_i32 s37, s3, 0xa000
	v_lshl_or_b32 v134, s10, 6, v189
	global_load_lds_dwordx4 v[6:7], off
	v_lshl_add_u64 v[4:5], v[4:5], 0, s[14:15]
	s_mov_b32 m0, s36
	s_add_u32 s10, s4, 0x40080
	global_load_lds_dwordx4 v[4:5], off
	v_lshl_add_u64 v[2:3], v[2:3], 0, s[14:15]
	s_mov_b32 m0, s37
	s_addc_u32 s11, s5, 0
	global_load_lds_dwordx4 v[2:3], off
	s_add_i32 m0, s3, 0x1c000
	v_lshl_add_u64 v[2:3], s[10:11], 0, v[164:165]
	global_load_lds_dwordx4 v[2:3], off
	v_lshl_add_u64 v[2:3], s[10:11], 0, v[174:175]
	s_add_i32 m0, s3, 0x1e000
	v_bitop3_b32 v136, s9, v15, v190 bitop3:0xf6
	global_load_lds_dwordx4 v[2:3], off
	v_lshlrev_b32_e32 v2, 14, v0
	s_lshl_b64 s[8:9], s[8:9], 17
	v_and_b32_e32 v2, 0xffff8000, v2
	s_and_b32 s9, s9, 0x1ffff
	s_and_b32 s8, s8, 0xfff80000
	v_lshl_add_u32 v2, v10, 11, v2
	v_and_b32_e32 v0, 1, v0
	v_readlane_b32 s10, v254, 37
	v_lshl_or_b32 v0, v0, 6, v2
	v_readlane_b32 s11, v254, 38
	s_add_u32 s8, s10, s8
	v_lshl_add_u32 v0, v11, 1, v0
	s_addc_u32 s9, s11, s9
	v_lshl_add_u64 v[130:131], s[8:9], 0, v[0:1]
	v_lshlrev_b32_e32 v0, 14, v12
	v_and_b32_e32 v0, 0xffff8000, v0
	v_lshl_add_u32 v0, v13, 11, v0
	v_and_b32_e32 v2, 1, v12
	s_waitcnt vmcnt(6)
	v_lshl_or_b32 v0, v2, 6, v0
	v_lshl_add_u32 v0, v14, 1, v0
	v_mov_b32_e32 v2, 0
	v_lshl_add_u64 v[132:133], s[8:9], 0, v[0:1]
	s_mov_b32 s38, -2
	s_mov_b64 s[8:9], 0xec40080
	v_add_u32_e32 v0, 0, v16
	s_barrier
	s_add_u32 s10, s8, 0xf13c0080
	s_addc_u32 s11, s9, -1
	s_cmp_lg_u32 s38, 12
	s_cselect_b32 s10, s10, 0
	s_cselect_b32 s11, s11, 0
	s_add_u32 s22, s6, s10
	s_addc_u32 s23, s7, s11
	s_add_i32 s39, 0, 0x10000
	s_add_u32 s10, s4, s10
	v_add_u32_e32 v137, s39, v136
	s_addc_u32 s11, s5, s11
	s_add_i32 s42, 0, 0x14000
	ds_read_b128 v[138:141], v137
	ds_read_b128 v[142:145], v137 offset:1024
	ds_read_b128 v[150:153], v137 offset:2048
	ds_read_b128 v[154:157], v137 offset:3072
	v_add_u32_e32 v137, s42, v136
	ds_read_b128 v[158:161], v137
	ds_read_b128 v[176:179], v137 offset:1024
	ds_read_b128 v[180:183], v137 offset:2048
	ds_read_b128 v[184:187], v137 offset:3072
	v_lshl_add_u64 v[166:167], v[130:131], 0, s[8:9]
	s_add_i32 m0, s3, 0xc000
	ds_read_b128 v[192:195], v0
	ds_read_b128 v[196:199], v0 offset:1024
	ds_read_b128 v[200:203], v0 offset:2048
	ds_read_b128 v[214:217], v0 offset:3072
	ds_read_b128 v[218:221], v0 offset:4096
	ds_read_b128 v[222:225], v0 offset:5120
	ds_read_b128 v[226:229], v0 offset:6144
	ds_read_b128 v[230:233], v0 offset:7168
	global_load_lds_dwordx4 v[166:167], off
	v_lshl_add_u64 v[166:167], v[132:133], 0, s[8:9]
	s_add_i32 m0, s3, 0xe000
	s_nop 0
	global_load_lds_dwordx4 v[166:167], off
	s_waitcnt vmcnt(8)
	s_waitcnt lgkmcnt(0)
	s_barrier
	s_setprio 1
	s_waitcnt lgkmcnt(0)
	v_mfma_f32_16x16x32_bf16 v[126:129], v[138:141], v[192:195], 0
	v_mfma_f32_16x16x32_bf16 v[122:125], v[150:153], v[192:195], 0
	v_mfma_f32_16x16x32_bf16 v[110:113], v[138:141], v[200:203], 0
	v_mfma_f32_16x16x32_bf16 v[106:109], v[150:153], v[200:203], 0
	v_mfma_f32_16x16x32_bf16 v[94:97], v[138:141], v[218:221], 0
	v_mfma_f32_16x16x32_bf16 v[90:93], v[150:153], v[218:221], 0
	v_mfma_f32_16x16x32_bf16 v[78:81], v[138:141], v[226:229], 0
	v_mfma_f32_16x16x32_bf16 v[74:77], v[150:153], v[226:229], 0
	v_mfma_f32_16x16x32_bf16 v[126:129], v[142:145], v[196:199], v[126:129]
	v_mfma_f32_16x16x32_bf16 v[122:125], v[154:157], v[196:199], v[122:125]
	v_mfma_f32_16x16x32_bf16 v[110:113], v[142:145], v[214:217], v[110:113]
	v_mfma_f32_16x16x32_bf16 v[106:109], v[154:157], v[214:217], v[106:109]
	v_mfma_f32_16x16x32_bf16 v[94:97], v[142:145], v[222:225], v[94:97]
	v_mfma_f32_16x16x32_bf16 v[90:93], v[154:157], v[222:225], v[90:93]
	v_mfma_f32_16x16x32_bf16 v[78:81], v[142:145], v[230:233], v[78:81]
	v_mfma_f32_16x16x32_bf16 v[74:77], v[154:157], v[230:233], v[74:77]
	s_setprio 0
	s_setprio 1
	v_mfma_f32_16x16x32_bf16 v[118:121], v[158:161], v[192:195], 0
	v_mfma_f32_16x16x32_bf16 v[114:117], v[180:183], v[192:195], 0
	v_mfma_f32_16x16x32_bf16 v[102:105], v[158:161], v[200:203], 0
	v_mfma_f32_16x16x32_bf16 v[98:101], v[180:183], v[200:203], 0
	v_mfma_f32_16x16x32_bf16 v[86:89], v[158:161], v[218:221], 0
	v_mfma_f32_16x16x32_bf16 v[82:85], v[180:183], v[218:221], 0
	v_mfma_f32_16x16x32_bf16 v[70:73], v[158:161], v[226:229], 0
	v_mfma_f32_16x16x32_bf16 v[66:69], v[180:183], v[226:229], 0
	v_mfma_f32_16x16x32_bf16 v[118:121], v[176:179], v[196:199], v[118:121]
	v_mfma_f32_16x16x32_bf16 v[114:117], v[184:187], v[196:199], v[114:117]
	v_mfma_f32_16x16x32_bf16 v[102:105], v[176:179], v[214:217], v[102:105]
	v_mfma_f32_16x16x32_bf16 v[98:101], v[184:187], v[214:217], v[98:101]
	v_mfma_f32_16x16x32_bf16 v[86:89], v[176:179], v[222:225], v[86:89]
	v_mfma_f32_16x16x32_bf16 v[82:85], v[184:187], v[222:225], v[82:85]
	v_mfma_f32_16x16x32_bf16 v[70:73], v[176:179], v[230:233], v[70:73]
	v_mfma_f32_16x16x32_bf16 v[66:69], v[184:187], v[230:233], v[66:69]
	s_setprio 0
	s_barrier
	s_add_i32 s39, s39, s29
	v_lshl_add_u64 v[166:167], s[10:11], 0, v[164:165]
	s_mov_b32 m0, s39
	ds_read_b128 v[192:195], v0 offset:16384
	ds_read_b128 v[196:199], v0 offset:17408
	ds_read_b128 v[200:203], v0 offset:18432
	ds_read_b128 v[214:217], v0 offset:19456
	ds_read_b128 v[218:221], v0 offset:20480
	ds_read_b128 v[222:225], v0 offset:21504
	ds_read_b128 v[226:229], v0 offset:22528
	ds_read_b128 v[230:233], v0 offset:23552
	global_load_lds_dwordx4 v[166:167], off
	s_add_i32 m0, s39, 0x2000
	s_add_u32 s40, s10, 0x40000
	v_lshl_add_u64 v[204:205], s[10:11], 0, v[174:175]
	s_addc_u32 s41, s11, 0
	s_add_i32 s39, s42, s29
	global_load_lds_dwordx4 v[204:205], off
	v_lshl_add_u64 v[234:235], s[40:41], 0, v[164:165]
	s_mov_b32 m0, s39
	v_lshl_add_u64 v[236:237], s[22:23], 0, v[172:173]
	global_load_lds_dwordx4 v[234:235], off
	v_lshl_add_u64 v[234:235], s[40:41], 0, v[174:175]
	s_add_i32 m0, s39, 0x2000
	s_nop 0
	global_load_lds_dwordx4 v[234:235], off
	v_lshl_add_u64 v[234:235], s[22:23], 0, v[162:163]
	s_mov_b32 m0, s3
	s_nop 0
	global_load_lds_dwordx4 v[234:235], off
	s_mov_b32 m0, s30
	s_nop 0
	global_load_lds_dwordx4 v[236:237], off
	s_waitcnt vmcnt(8)
	s_waitcnt lgkmcnt(0)
	s_barrier
	s_setprio 1
	s_waitcnt lgkmcnt(0)
	v_mfma_f32_16x16x32_bf16 v[62:65], v[138:141], v[192:195], 0
	v_mfma_f32_16x16x32_bf16 v[58:61], v[150:153], v[192:195], 0
	v_mfma_f32_16x16x32_bf16 v[46:49], v[138:141], v[200:203], 0
	v_mfma_f32_16x16x32_bf16 v[42:45], v[150:153], v[200:203], 0
	v_mfma_f32_16x16x32_bf16 v[30:33], v[138:141], v[218:221], 0
	v_mfma_f32_16x16x32_bf16 v[26:29], v[150:153], v[218:221], 0
	v_mfma_f32_16x16x32_bf16 v[14:17], v[138:141], v[226:229], 0
	v_mfma_f32_16x16x32_bf16 v[10:13], v[150:153], v[226:229], 0
	v_mfma_f32_16x16x32_bf16 v[62:65], v[142:145], v[196:199], v[62:65]
	v_mfma_f32_16x16x32_bf16 v[58:61], v[154:157], v[196:199], v[58:61]
	v_mfma_f32_16x16x32_bf16 v[46:49], v[142:145], v[214:217], v[46:49]
	v_mfma_f32_16x16x32_bf16 v[42:45], v[154:157], v[214:217], v[42:45]
	v_mfma_f32_16x16x32_bf16 v[30:33], v[142:145], v[222:225], v[30:33]
	v_mfma_f32_16x16x32_bf16 v[26:29], v[154:157], v[222:225], v[26:29]
	v_mfma_f32_16x16x32_bf16 v[14:17], v[142:145], v[230:233], v[14:17]
	v_mfma_f32_16x16x32_bf16 v[10:13], v[154:157], v[230:233], v[10:13]
	s_setprio 0
	s_setprio 1
	v_mfma_f32_16x16x32_bf16 v[54:57], v[158:161], v[192:195], 0
	v_mfma_f32_16x16x32_bf16 v[50:53], v[180:183], v[192:195], 0
	v_mfma_f32_16x16x32_bf16 v[38:41], v[158:161], v[200:203], 0
	v_mfma_f32_16x16x32_bf16 v[34:37], v[180:183], v[200:203], 0
	v_mfma_f32_16x16x32_bf16 v[22:25], v[158:161], v[218:221], 0
	v_mfma_f32_16x16x32_bf16 v[18:21], v[180:183], v[218:221], 0
	v_mfma_f32_16x16x32_bf16 v[6:9], v[158:161], v[226:229], 0
	v_mfma_f32_16x16x32_bf16 v[2:5], v[180:183], v[226:229], 0
	v_mfma_f32_16x16x32_bf16 v[54:57], v[176:179], v[196:199], v[54:57]
	v_mfma_f32_16x16x32_bf16 v[50:53], v[184:187], v[196:199], v[50:53]
	v_mfma_f32_16x16x32_bf16 v[38:41], v[176:179], v[214:217], v[38:41]
	v_mfma_f32_16x16x32_bf16 v[34:37], v[184:187], v[214:217], v[34:37]
	v_mfma_f32_16x16x32_bf16 v[22:25], v[176:179], v[222:225], v[22:25]
	v_mfma_f32_16x16x32_bf16 v[18:21], v[184:187], v[222:225], v[18:21]
	v_mfma_f32_16x16x32_bf16 v[6:9], v[176:179], v[230:233], v[6:9]
	v_mfma_f32_16x16x32_bf16 v[2:5], v[184:187], v[230:233], v[2:5]
	s_setprio 0
	s_barrier
	s_add_i32 s39, 0, 0x18000
	v_add_u32_e32 v137, s39, v136
	s_add_i32 s40, 0, 0x1c000
	ds_read_b128 v[138:141], v137
	ds_read_b128 v[142:145], v137 offset:1024
	ds_read_b128 v[150:153], v137 offset:2048
	ds_read_b128 v[154:157], v137 offset:3072
	v_add_u32_e32 v137, s40, v136
	ds_read_b128 v[158:161], v137
	ds_read_b128 v[176:179], v137 offset:1024
	ds_read_b128 v[180:183], v137 offset:2048
	ds_read_b128 v[184:187], v137 offset:3072
	s_add_u32 s22, s22, 0x40000
	s_addc_u32 s23, s23, 0
	s_mov_b32 m0, s31
	v_lshl_add_u64 v[238:239], s[22:23], 0, v[162:163]
	ds_read_b128 v[192:195], v0 offset:32768
	ds_read_b128 v[196:199], v0 offset:33792
	ds_read_b128 v[200:203], v0 offset:34816
	ds_read_b128 v[214:217], v0 offset:35840
	ds_read_b128 v[218:221], v0 offset:36864
	ds_read_b128 v[222:225], v0 offset:37888
	ds_read_b128 v[226:229], v0 offset:38912
	ds_read_b128 v[230:233], v0 offset:39936
	global_load_lds_dwordx4 v[238:239], off
	v_lshl_add_u64 v[238:239], s[22:23], 0, v[172:173]
	s_mov_b32 m0, s34
	s_nop 0
	global_load_lds_dwordx4 v[238:239], off
	s_waitcnt vmcnt(8)
	s_waitcnt lgkmcnt(0)
	s_barrier
	s_setprio 1
	s_waitcnt lgkmcnt(0)
	v_mfma_f32_16x16x32_bf16 v[126:129], v[138:141], v[192:195], v[126:129]
	v_mfma_f32_16x16x32_bf16 v[122:125], v[150:153], v[192:195], v[122:125]
	v_mfma_f32_16x16x32_bf16 v[110:113], v[138:141], v[200:203], v[110:113]
	v_mfma_f32_16x16x32_bf16 v[106:109], v[150:153], v[200:203], v[106:109]
	v_mfma_f32_16x16x32_bf16 v[94:97], v[138:141], v[218:221], v[94:97]
	v_mfma_f32_16x16x32_bf16 v[90:93], v[150:153], v[218:221], v[90:93]
	v_mfma_f32_16x16x32_bf16 v[78:81], v[138:141], v[226:229], v[78:81]
	v_mfma_f32_16x16x32_bf16 v[74:77], v[150:153], v[226:229], v[74:77]
	v_mfma_f32_16x16x32_bf16 v[126:129], v[142:145], v[196:199], v[126:129]
	v_mfma_f32_16x16x32_bf16 v[122:125], v[154:157], v[196:199], v[122:125]
	v_mfma_f32_16x16x32_bf16 v[110:113], v[142:145], v[214:217], v[110:113]
	v_mfma_f32_16x16x32_bf16 v[106:109], v[154:157], v[214:217], v[106:109]
	v_mfma_f32_16x16x32_bf16 v[94:97], v[142:145], v[222:225], v[94:97]
	v_mfma_f32_16x16x32_bf16 v[90:93], v[154:157], v[222:225], v[90:93]
	v_mfma_f32_16x16x32_bf16 v[78:81], v[142:145], v[230:233], v[78:81]
	v_mfma_f32_16x16x32_bf16 v[74:77], v[154:157], v[230:233], v[74:77]
	s_setprio 0
	s_setprio 1
	v_mfma_f32_16x16x32_bf16 v[118:121], v[158:161], v[192:195], v[118:121]
	v_mfma_f32_16x16x32_bf16 v[114:117], v[180:183], v[192:195], v[114:117]
	v_mfma_f32_16x16x32_bf16 v[102:105], v[158:161], v[200:203], v[102:105]
	v_mfma_f32_16x16x32_bf16 v[98:101], v[180:183], v[200:203], v[98:101]
	v_mfma_f32_16x16x32_bf16 v[86:89], v[158:161], v[218:221], v[86:89]
	v_mfma_f32_16x16x32_bf16 v[82:85], v[180:183], v[218:221], v[82:85]
	v_mfma_f32_16x16x32_bf16 v[70:73], v[158:161], v[226:229], v[70:73]
	v_mfma_f32_16x16x32_bf16 v[66:69], v[180:183], v[226:229], v[66:69]
	v_mfma_f32_16x16x32_bf16 v[118:121], v[176:179], v[196:199], v[118:121]
	v_mfma_f32_16x16x32_bf16 v[114:117], v[184:187], v[196:199], v[114:117]
	v_mfma_f32_16x16x32_bf16 v[102:105], v[176:179], v[214:217], v[102:105]
	v_mfma_f32_16x16x32_bf16 v[98:101], v[184:187], v[214:217], v[98:101]
	v_mfma_f32_16x16x32_bf16 v[86:89], v[176:179], v[222:225], v[86:89]
	v_mfma_f32_16x16x32_bf16 v[82:85], v[184:187], v[222:225], v[82:85]
	v_mfma_f32_16x16x32_bf16 v[70:73], v[176:179], v[230:233], v[70:73]
	v_mfma_f32_16x16x32_bf16 v[66:69], v[184:187], v[230:233], v[66:69]
	s_setprio 0
	s_barrier
	s_add_i32 s22, s39, s29
	v_lshl_add_u64 v[166:167], v[166:167], 0, s[14:15]
	s_mov_b32 m0, s22
	ds_read_b128 v[192:195], v0 offset:49152
	ds_read_b128 v[196:199], v0 offset:50176
	ds_read_b128 v[200:203], v0 offset:51200
	ds_read_b128 v[214:217], v0 offset:52224
	ds_read_b128 v[218:221], v0 offset:53248
	ds_read_b128 v[222:225], v0 offset:54272
	ds_read_b128 v[226:229], v0 offset:55296
	ds_read_b128 v[230:233], v0 offset:56320
	global_load_lds_dwordx4 v[166:167], off
	s_add_i32 m0, s22, 0x2000
	s_add_u32 s10, s10, 0x40080
	v_lshl_add_u64 v[166:167], v[204:205], 0, s[14:15]
	s_addc_u32 s11, s11, 0
	s_add_i32 s22, s40, s29
	global_load_lds_dwordx4 v[166:167], off
	v_lshl_add_u64 v[166:167], s[10:11], 0, v[164:165]
	s_mov_b32 m0, s22
	s_nop 0
	global_load_lds_dwordx4 v[166:167], off
	v_lshl_add_u64 v[166:167], s[10:11], 0, v[174:175]
	s_add_i32 m0, s22, 0x2000
	s_nop 0
	global_load_lds_dwordx4 v[166:167], off
	v_lshl_add_u64 v[166:167], v[234:235], 0, s[14:15]
	s_mov_b32 m0, s36
	s_nop 0
	global_load_lds_dwordx4 v[166:167], off
	v_lshl_add_u64 v[166:167], v[236:237], 0, s[14:15]
	s_mov_b32 m0, s37
	s_nop 0
	global_load_lds_dwordx4 v[166:167], off
	s_waitcnt vmcnt(8)
	s_waitcnt lgkmcnt(0)
	s_barrier
	s_setprio 1
	s_waitcnt lgkmcnt(0)
	v_mfma_f32_16x16x32_bf16 v[62:65], v[138:141], v[192:195], v[62:65]
	v_mfma_f32_16x16x32_bf16 v[58:61], v[150:153], v[192:195], v[58:61]
	v_mfma_f32_16x16x32_bf16 v[46:49], v[138:141], v[200:203], v[46:49]
	v_mfma_f32_16x16x32_bf16 v[42:45], v[150:153], v[200:203], v[42:45]
	v_mfma_f32_16x16x32_bf16 v[30:33], v[138:141], v[218:221], v[30:33]
	v_mfma_f32_16x16x32_bf16 v[26:29], v[150:153], v[218:221], v[26:29]
	v_mfma_f32_16x16x32_bf16 v[14:17], v[138:141], v[226:229], v[14:17]
	v_mfma_f32_16x16x32_bf16 v[10:13], v[150:153], v[226:229], v[10:13]
	v_mfma_f32_16x16x32_bf16 v[62:65], v[142:145], v[196:199], v[62:65]
	v_mfma_f32_16x16x32_bf16 v[58:61], v[154:157], v[196:199], v[58:61]
	v_mfma_f32_16x16x32_bf16 v[46:49], v[142:145], v[214:217], v[46:49]
	v_mfma_f32_16x16x32_bf16 v[42:45], v[154:157], v[214:217], v[42:45]
	v_mfma_f32_16x16x32_bf16 v[30:33], v[142:145], v[222:225], v[30:33]
	v_mfma_f32_16x16x32_bf16 v[26:29], v[154:157], v[222:225], v[26:29]
	v_mfma_f32_16x16x32_bf16 v[14:17], v[142:145], v[230:233], v[14:17]
	v_mfma_f32_16x16x32_bf16 v[10:13], v[154:157], v[230:233], v[10:13]
	s_setprio 0
	s_setprio 1
	v_mfma_f32_16x16x32_bf16 v[54:57], v[158:161], v[192:195], v[54:57]
	v_mfma_f32_16x16x32_bf16 v[50:53], v[180:183], v[192:195], v[50:53]
	v_mfma_f32_16x16x32_bf16 v[38:41], v[158:161], v[200:203], v[38:41]
	v_mfma_f32_16x16x32_bf16 v[34:37], v[180:183], v[200:203], v[34:37]
	v_mfma_f32_16x16x32_bf16 v[22:25], v[158:161], v[218:221], v[22:25]
	v_mfma_f32_16x16x32_bf16 v[18:21], v[180:183], v[218:221], v[18:21]
	v_mfma_f32_16x16x32_bf16 v[6:9], v[158:161], v[226:229], v[6:9]
	v_mfma_f32_16x16x32_bf16 v[2:5], v[180:183], v[226:229], v[2:5]
	v_mfma_f32_16x16x32_bf16 v[54:57], v[176:179], v[196:199], v[54:57]
	v_mfma_f32_16x16x32_bf16 v[50:53], v[184:187], v[196:199], v[50:53]
	v_mfma_f32_16x16x32_bf16 v[38:41], v[176:179], v[214:217], v[38:41]
	v_mfma_f32_16x16x32_bf16 v[34:37], v[184:187], v[214:217], v[34:37]
	v_mfma_f32_16x16x32_bf16 v[22:25], v[176:179], v[222:225], v[22:25]
	v_mfma_f32_16x16x32_bf16 v[18:21], v[184:187], v[222:225], v[18:21]
	v_mfma_f32_16x16x32_bf16 v[6:9], v[176:179], v[230:233], v[6:9]
	v_mfma_f32_16x16x32_bf16 v[2:5], v[184:187], v[230:233], v[2:5]
	s_setprio 0
	s_barrier
	s_add_i32 s38, s38, 2
	s_add_u32 s8, s8, 0x100
	s_addc_u32 s9, s9, 0
	s_cmp_gt_u32 s38, 13
	s_cbranch_scc1 .Lpeel_k69_exit

.Lpeel_k69_exit:
	s_cmpk_lt_u32 s27, 0x100
	s_cbranch_scc0 .LBB0_72
	s_barrier

.LBB0_373:
	s_add_u32 s40, s40, 0x80
	s_addc_u32 s41, s41, 0
	s_add_u32 s34, s42, 0x100
	v_mov_b32_e32 v2, 0
	s_addc_u32 s48, s43, 0
	s_mov_b32 s42, 0
	s_cmp_eq_u32 s60, 1
	s_cbranch_scc1 .Ltb_res_skip
	s_cmp_eq_u32 s6, 0
	s_cbranch_scc1 .Ltb_res_skip
	s_barrier
.Ltb_res_skip:
	s_add_i32 s49, s42, 2
	s_add_u32 s74, s40, 0x80
	s_addc_u32 s43, s41, 0
	s_add_i32 s76, 0, 0x10000
	s_cmp_eq_u32 s67, s42
	s_cselect_b32 s43, s3, s43
	s_cselect_b32 s42, s2, s74
	s_cselect_b32 s75, s47, s48
	s_cselect_b32 s74, s46, s34
	s_add_i32 s77, 0, 0x14000
	v_add_u32_e32 v142, s76, v196
	v_add_u32_e32 v166, s77, v196
	ds_read_b128 v[122:125], v142
	ds_read_b128 v[134:137], v142 offset:1024
	ds_read_b128 v[138:141], v142 offset:2048
	ds_read_b128 v[142:145], v142 offset:3072
	ds_read_b128 v[150:153], v166
	ds_read_b128 v[154:157], v166 offset:1024
	ds_read_b128 v[158:161], v166 offset:2048
	ds_read_b128 v[178:181], v166 offset:3072
	v_lshl_add_u64 v[166:167], s[40:41], 0, v[174:175]
	s_add_i32 m0, s54, 0xc000
	ds_read_b128 v[182:185], v200
	ds_read_b128 v[186:189], v200 offset:1024
	ds_read_b128 v[190:193], v200 offset:2048
	ds_read_b128 v[202:205], v200 offset:3072
	ds_read_b128 v[214:217], v200 offset:4096
	ds_read_b128 v[218:221], v200 offset:5120
	ds_read_b128 v[222:225], v200 offset:6144
	ds_read_b128 v[226:229], v200 offset:7168
	global_load_lds_dwordx4 v[166:167], off
	v_lshl_add_u64 v[166:167], s[40:41], 0, v[176:177]
	s_add_i32 m0, s54, 0xe000
	s_nop 0
	global_load_lds_dwordx4 v[166:167], off
	s_waitcnt vmcnt(8)
	s_waitcnt lgkmcnt(0)
	s_barrier
	s_setprio 1
	s_waitcnt lgkmcnt(0)
	v_mfma_f32_16x16x32_bf16 v[130:133], v[122:125], v[182:185], 0
	v_mfma_f32_16x16x32_bf16 v[126:129], v[138:141], v[182:185], 0
	v_mfma_f32_16x16x32_bf16 v[110:113], v[122:125], v[190:193], 0
	v_mfma_f32_16x16x32_bf16 v[106:109], v[138:141], v[190:193], 0
	v_mfma_f32_16x16x32_bf16 v[94:97], v[122:125], v[214:217], 0
	v_mfma_f32_16x16x32_bf16 v[90:93], v[138:141], v[214:217], 0
	v_mfma_f32_16x16x32_bf16 v[78:81], v[122:125], v[222:225], 0
	v_mfma_f32_16x16x32_bf16 v[74:77], v[138:141], v[222:225], 0
	v_mfma_f32_16x16x32_bf16 v[130:133], v[134:137], v[186:189], v[130:133]
	v_mfma_f32_16x16x32_bf16 v[126:129], v[142:145], v[186:189], v[126:129]
	v_mfma_f32_16x16x32_bf16 v[110:113], v[134:137], v[202:205], v[110:113]
	v_mfma_f32_16x16x32_bf16 v[106:109], v[142:145], v[202:205], v[106:109]
	v_mfma_f32_16x16x32_bf16 v[94:97], v[134:137], v[218:221], v[94:97]
	v_mfma_f32_16x16x32_bf16 v[90:93], v[142:145], v[218:221], v[90:93]
	v_mfma_f32_16x16x32_bf16 v[78:81], v[134:137], v[226:229], v[78:81]
	v_mfma_f32_16x16x32_bf16 v[74:77], v[142:145], v[226:229], v[74:77]
	s_setprio 0
	s_setprio 1
	v_mfma_f32_16x16x32_bf16 v[118:121], v[150:153], v[182:185], 0
	v_mfma_f32_16x16x32_bf16 v[114:117], v[158:161], v[182:185], 0
	v_mfma_f32_16x16x32_bf16 v[102:105], v[150:153], v[190:193], 0
	v_mfma_f32_16x16x32_bf16 v[98:101], v[158:161], v[190:193], 0
	v_mfma_f32_16x16x32_bf16 v[86:89], v[150:153], v[214:217], 0
	v_mfma_f32_16x16x32_bf16 v[82:85], v[158:161], v[214:217], 0
	v_mfma_f32_16x16x32_bf16 v[70:73], v[150:153], v[222:225], 0
	v_mfma_f32_16x16x32_bf16 v[66:69], v[158:161], v[222:225], 0
	v_mfma_f32_16x16x32_bf16 v[118:121], v[154:157], v[186:189], v[118:121]
	v_mfma_f32_16x16x32_bf16 v[114:117], v[178:181], v[186:189], v[114:117]
	v_mfma_f32_16x16x32_bf16 v[102:105], v[154:157], v[202:205], v[102:105]
	v_mfma_f32_16x16x32_bf16 v[98:101], v[178:181], v[202:205], v[98:101]
	v_mfma_f32_16x16x32_bf16 v[86:89], v[154:157], v[218:221], v[86:89]
	v_mfma_f32_16x16x32_bf16 v[82:85], v[178:181], v[218:221], v[82:85]
	v_mfma_f32_16x16x32_bf16 v[70:73], v[154:157], v[226:229], v[70:73]
	v_mfma_f32_16x16x32_bf16 v[66:69], v[178:181], v[226:229], v[66:69]
	s_setprio 0
	s_barrier
	s_add_i32 s76, s76, s51
	v_lshl_add_u64 v[166:167], s[74:75], 0, v[0:1]
	s_mov_b32 m0, s76
	ds_read_b128 v[182:185], v200 offset:16384
	ds_read_b128 v[186:189], v200 offset:17408
	ds_read_b128 v[190:193], v200 offset:18432
	ds_read_b128 v[202:205], v200 offset:19456
	ds_read_b128 v[214:217], v200 offset:20480
	ds_read_b128 v[218:221], v200 offset:21504
	ds_read_b128 v[222:225], v200 offset:22528
	ds_read_b128 v[226:229], v200 offset:23552
	global_load_lds_dwordx4 v[166:167], off
	s_add_i32 m0, s76, 0x2000
	v_lshl_add_u64 v[194:195], s[74:75], 0, v[172:173]
	s_add_u32 s74, s74, s16
	s_addc_u32 s75, s75, 0
	s_add_i32 s76, s77, s51
	global_load_lds_dwordx4 v[194:195], off
	v_lshl_add_u64 v[230:231], s[74:75], 0, v[0:1]
	s_mov_b32 m0, s76
	v_lshl_add_u64 v[232:233], s[74:75], 0, v[172:173]
	global_load_lds_dwordx4 v[230:231], off
	s_add_i32 m0, s76, 0x2000
	v_lshl_add_u64 v[234:235], s[42:43], 0, v[162:163]
	global_load_lds_dwordx4 v[232:233], off
	s_mov_b32 m0, s54
	v_lshl_add_u64 v[236:237], s[42:43], 0, v[164:165]
	global_load_lds_dwordx4 v[234:235], off
	s_mov_b32 m0, s55
	s_nop 0
	global_load_lds_dwordx4 v[236:237], off
	s_waitcnt vmcnt(8)
	s_waitcnt lgkmcnt(0)
	s_barrier
	s_setprio 1
	s_waitcnt lgkmcnt(0)
	v_mfma_f32_16x16x32_bf16 v[62:65], v[122:125], v[182:185], 0
	v_mfma_f32_16x16x32_bf16 v[58:61], v[138:141], v[182:185], 0
	v_mfma_f32_16x16x32_bf16 v[46:49], v[122:125], v[190:193], 0
	v_mfma_f32_16x16x32_bf16 v[42:45], v[138:141], v[190:193], 0
	v_mfma_f32_16x16x32_bf16 v[30:33], v[122:125], v[214:217], 0
	v_mfma_f32_16x16x32_bf16 v[26:29], v[138:141], v[214:217], 0
	v_mfma_f32_16x16x32_bf16 v[14:17], v[122:125], v[222:225], 0
	v_mfma_f32_16x16x32_bf16 v[10:13], v[138:141], v[222:225], 0
	v_mfma_f32_16x16x32_bf16 v[62:65], v[134:137], v[186:189], v[62:65]
	v_mfma_f32_16x16x32_bf16 v[58:61], v[142:145], v[186:189], v[58:61]
	v_mfma_f32_16x16x32_bf16 v[46:49], v[134:137], v[202:205], v[46:49]
	v_mfma_f32_16x16x32_bf16 v[42:45], v[142:145], v[202:205], v[42:45]
	v_mfma_f32_16x16x32_bf16 v[30:33], v[134:137], v[218:221], v[30:33]
	v_mfma_f32_16x16x32_bf16 v[26:29], v[142:145], v[218:221], v[26:29]
	v_mfma_f32_16x16x32_bf16 v[14:17], v[134:137], v[226:229], v[14:17]
	v_mfma_f32_16x16x32_bf16 v[10:13], v[142:145], v[226:229], v[10:13]
	s_setprio 0
	s_setprio 1
	v_mfma_f32_16x16x32_bf16 v[54:57], v[150:153], v[182:185], 0
	v_mfma_f32_16x16x32_bf16 v[50:53], v[158:161], v[182:185], 0
	v_mfma_f32_16x16x32_bf16 v[38:41], v[150:153], v[190:193], 0
	v_mfma_f32_16x16x32_bf16 v[34:37], v[158:161], v[190:193], 0
	v_mfma_f32_16x16x32_bf16 v[22:25], v[150:153], v[214:217], 0
	v_mfma_f32_16x16x32_bf16 v[18:21], v[158:161], v[214:217], 0
	v_mfma_f32_16x16x32_bf16 v[6:9], v[150:153], v[222:225], 0
	v_mfma_f32_16x16x32_bf16 v[2:5], v[158:161], v[222:225], 0
	v_mfma_f32_16x16x32_bf16 v[54:57], v[154:157], v[186:189], v[54:57]
	v_mfma_f32_16x16x32_bf16 v[50:53], v[178:181], v[186:189], v[50:53]
	v_mfma_f32_16x16x32_bf16 v[38:41], v[154:157], v[202:205], v[38:41]
	v_mfma_f32_16x16x32_bf16 v[34:37], v[178:181], v[202:205], v[34:37]
	v_mfma_f32_16x16x32_bf16 v[22:25], v[154:157], v[218:221], v[22:25]
	v_mfma_f32_16x16x32_bf16 v[18:21], v[178:181], v[218:221], v[18:21]
	v_mfma_f32_16x16x32_bf16 v[6:9], v[154:157], v[226:229], v[6:9]
	v_mfma_f32_16x16x32_bf16 v[2:5], v[178:181], v[226:229], v[2:5]
	s_setprio 0
	s_barrier
	s_add_i32 s74, 0, 0x18000
	s_add_i32 s75, 0, 0x1c000
	v_add_u32_e32 v142, s74, v196
	v_add_u32_e32 v178, s75, v196
	ds_read_b128 v[122:125], v142
	ds_read_b128 v[134:137], v142 offset:1024
	ds_read_b128 v[138:141], v142 offset:2048
	ds_read_b128 v[142:145], v142 offset:3072
	ds_read_b128 v[150:153], v178
	ds_read_b128 v[154:157], v178 offset:1024
	ds_read_b128 v[158:161], v178 offset:2048
	ds_read_b128 v[178:181], v178 offset:3072
	s_add_u32 s42, s42, s16
	s_addc_u32 s43, s43, 0
	s_mov_b32 m0, s58
	v_lshl_add_u64 v[238:239], s[42:43], 0, v[162:163]
	ds_read_b128 v[182:185], v200 offset:32768
	ds_read_b128 v[186:189], v200 offset:33792
	ds_read_b128 v[190:193], v200 offset:34816
	ds_read_b128 v[202:205], v200 offset:35840
	ds_read_b128 v[214:217], v200 offset:36864
	ds_read_b128 v[218:221], v200 offset:37888
	ds_read_b128 v[222:225], v200 offset:38912
	ds_read_b128 v[226:229], v200 offset:39936
	global_load_lds_dwordx4 v[238:239], off
	v_lshl_add_u64 v[238:239], s[42:43], 0, v[164:165]
	s_mov_b32 m0, s59
	s_nop 0
	global_load_lds_dwordx4 v[238:239], off
	s_waitcnt vmcnt(8)
	s_waitcnt lgkmcnt(0)
	s_barrier
	s_setprio 1
	s_waitcnt lgkmcnt(0)
	v_mfma_f32_16x16x32_bf16 v[130:133], v[122:125], v[182:185], v[130:133]
	v_mfma_f32_16x16x32_bf16 v[126:129], v[138:141], v[182:185], v[126:129]
	v_mfma_f32_16x16x32_bf16 v[110:113], v[122:125], v[190:193], v[110:113]
	v_mfma_f32_16x16x32_bf16 v[106:109], v[138:141], v[190:193], v[106:109]
	v_mfma_f32_16x16x32_bf16 v[94:97], v[122:125], v[214:217], v[94:97]
	v_mfma_f32_16x16x32_bf16 v[90:93], v[138:141], v[214:217], v[90:93]
	v_mfma_f32_16x16x32_bf16 v[78:81], v[122:125], v[222:225], v[78:81]
	v_mfma_f32_16x16x32_bf16 v[74:77], v[138:141], v[222:225], v[74:77]
	v_mfma_f32_16x16x32_bf16 v[130:133], v[134:137], v[186:189], v[130:133]
	v_mfma_f32_16x16x32_bf16 v[126:129], v[142:145], v[186:189], v[126:129]
	v_mfma_f32_16x16x32_bf16 v[110:113], v[134:137], v[202:205], v[110:113]
	v_mfma_f32_16x16x32_bf16 v[106:109], v[142:145], v[202:205], v[106:109]
	v_mfma_f32_16x16x32_bf16 v[94:97], v[134:137], v[218:221], v[94:97]
	v_mfma_f32_16x16x32_bf16 v[90:93], v[142:145], v[218:221], v[90:93]
	v_mfma_f32_16x16x32_bf16 v[78:81], v[134:137], v[226:229], v[78:81]
	v_mfma_f32_16x16x32_bf16 v[74:77], v[142:145], v[226:229], v[74:77]
	s_setprio 0
	s_setprio 1
	v_mfma_f32_16x16x32_bf16 v[118:121], v[150:153], v[182:185], v[118:121]
	v_mfma_f32_16x16x32_bf16 v[114:117], v[158:161], v[182:185], v[114:117]
	v_mfma_f32_16x16x32_bf16 v[102:105], v[150:153], v[190:193], v[102:105]
	v_mfma_f32_16x16x32_bf16 v[98:101], v[158:161], v[190:193], v[98:101]
	v_mfma_f32_16x16x32_bf16 v[86:89], v[150:153], v[214:217], v[86:89]
	v_mfma_f32_16x16x32_bf16 v[82:85], v[158:161], v[214:217], v[82:85]
	v_mfma_f32_16x16x32_bf16 v[70:73], v[150:153], v[222:225], v[70:73]
	v_mfma_f32_16x16x32_bf16 v[66:69], v[158:161], v[222:225], v[66:69]
	v_mfma_f32_16x16x32_bf16 v[118:121], v[154:157], v[186:189], v[118:121]
	v_mfma_f32_16x16x32_bf16 v[114:117], v[178:181], v[186:189], v[114:117]
	v_mfma_f32_16x16x32_bf16 v[102:105], v[154:157], v[202:205], v[102:105]
	v_mfma_f32_16x16x32_bf16 v[98:101], v[178:181], v[202:205], v[98:101]
	v_mfma_f32_16x16x32_bf16 v[86:89], v[154:157], v[218:221], v[86:89]
	v_mfma_f32_16x16x32_bf16 v[82:85], v[178:181], v[218:221], v[82:85]
	v_mfma_f32_16x16x32_bf16 v[70:73], v[154:157], v[226:229], v[70:73]
	v_mfma_f32_16x16x32_bf16 v[66:69], v[178:181], v[226:229], v[66:69]
	s_setprio 0
	s_barrier
	s_add_i32 s42, s74, s51
	v_lshl_add_u64 v[166:167], v[166:167], 0, s[14:15]
	s_mov_b32 m0, s42
	ds_read_b128 v[182:185], v200 offset:49152
	ds_read_b128 v[186:189], v200 offset:50176
	ds_read_b128 v[190:193], v200 offset:51200
	ds_read_b128 v[202:205], v200 offset:52224
	ds_read_b128 v[214:217], v200 offset:53248
	ds_read_b128 v[218:221], v200 offset:54272
	ds_read_b128 v[222:225], v200 offset:55296
	ds_read_b128 v[226:229], v200 offset:56320
	global_load_lds_dwordx4 v[166:167], off
	v_lshl_add_u64 v[166:167], v[194:195], 0, s[14:15]
	s_add_i32 m0, s42, 0x2000
	s_add_i32 s42, s75, s51
	global_load_lds_dwordx4 v[166:167], off
	v_lshl_add_u64 v[166:167], v[230:231], 0, s[14:15]
	s_mov_b32 m0, s42
	s_nop 0
	global_load_lds_dwordx4 v[166:167], off
	v_lshl_add_u64 v[166:167], v[232:233], 0, s[14:15]
	s_add_i32 m0, s42, 0x2000
	s_nop 0
	global_load_lds_dwordx4 v[166:167], off
	v_lshl_add_u64 v[166:167], v[234:235], 0, s[14:15]
	s_mov_b32 m0, s65
	s_nop 0
	global_load_lds_dwordx4 v[166:167], off
	v_lshl_add_u64 v[166:167], v[236:237], 0, s[14:15]
	s_mov_b32 m0, s66
	s_nop 0
	global_load_lds_dwordx4 v[166:167], off
	s_waitcnt vmcnt(8)
	s_waitcnt lgkmcnt(0)
	s_barrier
	s_setprio 1
	s_waitcnt lgkmcnt(0)
	v_mfma_f32_16x16x32_bf16 v[62:65], v[122:125], v[182:185], v[62:65]
	v_mfma_f32_16x16x32_bf16 v[58:61], v[138:141], v[182:185], v[58:61]
	v_mfma_f32_16x16x32_bf16 v[46:49], v[122:125], v[190:193], v[46:49]
	v_mfma_f32_16x16x32_bf16 v[42:45], v[138:141], v[190:193], v[42:45]
	v_mfma_f32_16x16x32_bf16 v[30:33], v[122:125], v[214:217], v[30:33]
	v_mfma_f32_16x16x32_bf16 v[26:29], v[138:141], v[214:217], v[26:29]
	v_mfma_f32_16x16x32_bf16 v[14:17], v[122:125], v[222:225], v[14:17]
	v_mfma_f32_16x16x32_bf16 v[10:13], v[138:141], v[222:225], v[10:13]
	v_mfma_f32_16x16x32_bf16 v[62:65], v[134:137], v[186:189], v[62:65]
	v_mfma_f32_16x16x32_bf16 v[58:61], v[142:145], v[186:189], v[58:61]
	v_mfma_f32_16x16x32_bf16 v[46:49], v[134:137], v[202:205], v[46:49]
	v_mfma_f32_16x16x32_bf16 v[42:45], v[142:145], v[202:205], v[42:45]
	v_mfma_f32_16x16x32_bf16 v[30:33], v[134:137], v[218:221], v[30:33]
	v_mfma_f32_16x16x32_bf16 v[26:29], v[142:145], v[218:221], v[26:29]
	v_mfma_f32_16x16x32_bf16 v[14:17], v[134:137], v[226:229], v[14:17]
	v_mfma_f32_16x16x32_bf16 v[10:13], v[142:145], v[226:229], v[10:13]
	s_setprio 0
	s_setprio 1
	v_mfma_f32_16x16x32_bf16 v[54:57], v[150:153], v[182:185], v[54:57]
	v_mfma_f32_16x16x32_bf16 v[50:53], v[158:161], v[182:185], v[50:53]
	v_mfma_f32_16x16x32_bf16 v[38:41], v[150:153], v[190:193], v[38:41]
	v_mfma_f32_16x16x32_bf16 v[34:37], v[158:161], v[190:193], v[34:37]
	v_mfma_f32_16x16x32_bf16 v[22:25], v[150:153], v[214:217], v[22:25]
	v_mfma_f32_16x16x32_bf16 v[18:21], v[158:161], v[214:217], v[18:21]
	v_mfma_f32_16x16x32_bf16 v[6:9], v[150:153], v[222:225], v[6:9]
	v_mfma_f32_16x16x32_bf16 v[2:5], v[158:161], v[222:225], v[2:5]
	v_mfma_f32_16x16x32_bf16 v[54:57], v[154:157], v[186:189], v[54:57]
	v_mfma_f32_16x16x32_bf16 v[50:53], v[178:181], v[186:189], v[50:53]
	v_mfma_f32_16x16x32_bf16 v[38:41], v[154:157], v[202:205], v[38:41]
	v_mfma_f32_16x16x32_bf16 v[34:37], v[178:181], v[202:205], v[34:37]
	v_mfma_f32_16x16x32_bf16 v[22:25], v[154:157], v[218:221], v[22:25]
	v_mfma_f32_16x16x32_bf16 v[18:21], v[178:181], v[218:221], v[18:21]
	v_mfma_f32_16x16x32_bf16 v[6:9], v[154:157], v[226:229], v[6:9]
	v_mfma_f32_16x16x32_bf16 v[2:5], v[178:181], v[226:229], v[2:5]
	s_setprio 0
	s_barrier
	s_add_u32 s40, s40, 0x100
	s_addc_u32 s41, s41, 0
	s_add_u32 s34, s34, 0x100
	s_addc_u32 s48, s48, 0
	s_cmp_ge_u32 s49, s64
	s_mov_b32 s42, s49
	s_cbranch_scc1 .Lpeel_k374_exit

.Lpeel_k374_exit:
	s_and_b64 vcc, exec, s[22:23]
	s_cbranch_vccz .LBB0_377
	s_barrier

.LBB0_510:
	s_ashr_i32 s31, s30, 31
	s_lshl_b64 s[38:39], s[30:31], 19
	s_add_u32 s38, s20, s38
	s_addc_u32 s39, s21, s39
	s_and_b64 s[40:41], s[36:37], exec
	s_cselect_b32 s16, s39, s45
	s_cselect_b32 s29, s38, s44
	s_ashr_i32 s23, s22, 31
	s_lshl_b64 s[40:41], s[22:23], 19
	s_add_u32 s40, s26, s40
	s_addc_u32 s41, s27, s41
	s_and_b64 s[48:49], s[36:37], exec
	s_cselect_b32 s23, s41, s47
	s_cselect_b32 s31, s40, s46
	s_add_u32 s44, s44, 0x40080
	s_addc_u32 s45, s45, 0
	s_add_u32 s34, s46, 0x100
	v_mov_b32_e32 v2, 0
	s_addc_u32 s43, s47, 0
	s_mov_b32 s50, -2
	s_cmp_eq_u32 s3, 0
	s_cbranch_scc1 .Ltb_sw_skip
	s_cmp_eq_u32 s6, 0
	s_cbranch_scc1 .Ltb_sw_skip
	s_barrier
.Ltb_sw_skip:
	s_add_u32 s46, s44, 0xfffc0080
	s_addc_u32 s47, s45, -1
	s_add_i32 s51, 0, 0x10000
	s_cmp_eq_u32 s50, 12
	s_cselect_b32 s49, s16, s47
	s_cselect_b32 s48, s29, s46
	v_add_u32_e32 v0, s51, v198
	s_cselect_b32 s47, s23, s43
	s_cselect_b32 s46, s31, s34
	s_add_i32 s65, 0, 0x14000
	ds_read_b128 v[50:53], v0
	ds_read_b128 v[54:57], v0 offset:1024
	ds_read_b128 v[66:69], v0 offset:2048
	ds_read_b128 v[70:73], v0 offset:3072
	v_add_u32_e32 v0, s65, v198
	ds_read_b128 v[174:177], v0
	ds_read_b128 v[178:181], v0 offset:1024
	ds_read_b128 v[182:185], v0 offset:2048
	ds_read_b128 v[186:189], v0 offset:3072
	v_lshl_add_u64 v[166:167], s[44:45], 0, v[164:165]
	s_add_i32 m0, s52, 0xc000
	ds_read_b128 v[190:193], v203
	ds_read_b128 v[194:197], v203 offset:1024
	ds_read_b128 v[214:217], v203 offset:2048
	ds_read_b128 v[218:221], v203 offset:3072
	ds_read_b128 v[222:225], v203 offset:4096
	ds_read_b128 v[226:229], v203 offset:5120
	ds_read_b128 v[230:233], v203 offset:6144
	ds_read_b128 v[234:237], v203 offset:7168
	global_load_lds_dwordx4 v[166:167], off
	v_lshl_add_u64 v[166:167], s[44:45], 0, v[172:173]
	s_add_i32 m0, s52, 0xe000
	s_nop 0
	global_load_lds_dwordx4 v[166:167], off
	s_waitcnt vmcnt(8)
	s_waitcnt lgkmcnt(0)
	s_barrier
	s_setprio 1
	s_waitcnt lgkmcnt(0)
	v_mfma_f32_16x16x32_bf16 v[142:145], v[50:53], v[190:193], 0
	v_mfma_f32_16x16x32_bf16 v[138:141], v[66:69], v[190:193], 0
	v_mfma_f32_16x16x32_bf16 v[126:129], v[50:53], v[214:217], 0
	v_mfma_f32_16x16x32_bf16 v[122:125], v[66:69], v[214:217], 0
	v_mfma_f32_16x16x32_bf16 v[110:113], v[50:53], v[222:225], 0
	v_mfma_f32_16x16x32_bf16 v[106:109], v[66:69], v[222:225], 0
	v_mfma_f32_16x16x32_bf16 v[94:97], v[50:53], v[230:233], 0
	v_mfma_f32_16x16x32_bf16 v[90:93], v[66:69], v[230:233], 0
	v_mfma_f32_16x16x32_bf16 v[142:145], v[54:57], v[194:197], v[142:145]
	v_mfma_f32_16x16x32_bf16 v[138:141], v[70:73], v[194:197], v[138:141]
	v_mfma_f32_16x16x32_bf16 v[126:129], v[54:57], v[218:221], v[126:129]
	v_mfma_f32_16x16x32_bf16 v[122:125], v[70:73], v[218:221], v[122:125]
	v_mfma_f32_16x16x32_bf16 v[110:113], v[54:57], v[226:229], v[110:113]
	v_mfma_f32_16x16x32_bf16 v[106:109], v[70:73], v[226:229], v[106:109]
	v_mfma_f32_16x16x32_bf16 v[94:97], v[54:57], v[234:237], v[94:97]
	v_mfma_f32_16x16x32_bf16 v[90:93], v[70:73], v[234:237], v[90:93]
	s_setprio 0
	s_setprio 1
	v_mfma_f32_16x16x32_bf16 v[134:137], v[174:177], v[190:193], 0
	v_mfma_f32_16x16x32_bf16 v[130:133], v[182:185], v[190:193], 0
	v_mfma_f32_16x16x32_bf16 v[118:121], v[174:177], v[214:217], 0
	v_mfma_f32_16x16x32_bf16 v[114:117], v[182:185], v[214:217], 0
	v_mfma_f32_16x16x32_bf16 v[102:105], v[174:177], v[222:225], 0
	v_mfma_f32_16x16x32_bf16 v[98:101], v[182:185], v[222:225], 0
	v_mfma_f32_16x16x32_bf16 v[86:89], v[174:177], v[230:233], 0
	v_mfma_f32_16x16x32_bf16 v[82:85], v[182:185], v[230:233], 0
	v_mfma_f32_16x16x32_bf16 v[134:137], v[178:181], v[194:197], v[134:137]
	v_mfma_f32_16x16x32_bf16 v[130:133], v[186:189], v[194:197], v[130:133]
	v_mfma_f32_16x16x32_bf16 v[118:121], v[178:181], v[218:221], v[118:121]
	v_mfma_f32_16x16x32_bf16 v[114:117], v[186:189], v[218:221], v[114:117]
	v_mfma_f32_16x16x32_bf16 v[102:105], v[178:181], v[226:229], v[102:105]
	v_mfma_f32_16x16x32_bf16 v[98:101], v[186:189], v[226:229], v[98:101]
	v_mfma_f32_16x16x32_bf16 v[86:89], v[178:181], v[234:237], v[86:89]
	v_mfma_f32_16x16x32_bf16 v[82:85], v[186:189], v[234:237], v[82:85]
	s_setprio 0
	s_barrier
	s_add_i32 s51, s51, s12
	v_lshl_add_u64 v[166:167], s[46:47], 0, v[152:153]
	s_mov_b32 m0, s51
	ds_read_b128 v[190:193], v203 offset:16384
	ds_read_b128 v[194:197], v203 offset:17408
	ds_read_b128 v[214:217], v203 offset:18432
	ds_read_b128 v[218:221], v203 offset:19456
	ds_read_b128 v[222:225], v203 offset:20480
	ds_read_b128 v[226:229], v203 offset:21504
	ds_read_b128 v[230:233], v203 offset:22528
	ds_read_b128 v[234:237], v203 offset:23552
	global_load_lds_dwordx4 v[166:167], off
	s_add_i32 m0, s51, 0x2000
	s_add_u32 s66, s46, 0x40000
	v_lshl_add_u64 v[204:205], s[46:47], 0, v[156:157]
	s_addc_u32 s67, s47, 0
	s_add_i32 s51, s65, s12
	global_load_lds_dwordx4 v[204:205], off
	v_lshl_add_u64 v[238:239], s[66:67], 0, v[152:153]
	s_mov_b32 m0, s51
	v_lshl_add_u64 v[240:241], s[48:49], 0, v[154:155]
	global_load_lds_dwordx4 v[238:239], off
	v_lshl_add_u64 v[238:239], s[66:67], 0, v[156:157]
	s_add_i32 m0, s51, 0x2000
	s_nop 0
	global_load_lds_dwordx4 v[238:239], off
	v_lshl_add_u64 v[238:239], s[48:49], 0, v[150:151]
	s_mov_b32 m0, s52
	s_nop 0
	global_load_lds_dwordx4 v[238:239], off
	s_mov_b32 m0, s53
	s_nop 0
	global_load_lds_dwordx4 v[240:241], off
	s_waitcnt vmcnt(8)
	s_waitcnt lgkmcnt(0)
	s_barrier
	s_setprio 1
	s_waitcnt lgkmcnt(0)
	v_mfma_f32_16x16x32_bf16 v[78:81], v[50:53], v[190:193], 0
	v_mfma_f32_16x16x32_bf16 v[74:77], v[66:69], v[190:193], 0
	v_mfma_f32_16x16x32_bf16 v[46:49], v[50:53], v[214:217], 0
	v_mfma_f32_16x16x32_bf16 v[42:45], v[66:69], v[214:217], 0
	v_mfma_f32_16x16x32_bf16 v[30:33], v[50:53], v[222:225], 0
	v_mfma_f32_16x16x32_bf16 v[26:29], v[66:69], v[222:225], 0
	v_mfma_f32_16x16x32_bf16 v[14:17], v[50:53], v[230:233], 0
	v_mfma_f32_16x16x32_bf16 v[10:13], v[66:69], v[230:233], 0
	v_mfma_f32_16x16x32_bf16 v[78:81], v[54:57], v[194:197], v[78:81]
	v_mfma_f32_16x16x32_bf16 v[74:77], v[70:73], v[194:197], v[74:77]
	v_mfma_f32_16x16x32_bf16 v[46:49], v[54:57], v[218:221], v[46:49]
	v_mfma_f32_16x16x32_bf16 v[42:45], v[70:73], v[218:221], v[42:45]
	v_mfma_f32_16x16x32_bf16 v[30:33], v[54:57], v[226:229], v[30:33]
	v_mfma_f32_16x16x32_bf16 v[26:29], v[70:73], v[226:229], v[26:29]
	v_mfma_f32_16x16x32_bf16 v[14:17], v[54:57], v[234:237], v[14:17]
	v_mfma_f32_16x16x32_bf16 v[10:13], v[70:73], v[234:237], v[10:13]
	s_setprio 0
	s_setprio 1
	v_mfma_f32_16x16x32_bf16 v[38:41], v[174:177], v[214:217], 0
	v_mfma_f32_16x16x32_bf16 v[34:37], v[182:185], v[214:217], 0
	v_mfma_f32_16x16x32_bf16 v[22:25], v[174:177], v[222:225], 0
	v_mfma_f32_16x16x32_bf16 v[18:21], v[182:185], v[222:225], 0
	v_mfma_f32_16x16x32_bf16 v[6:9], v[174:177], v[230:233], 0
	v_mfma_f32_16x16x32_bf16 v[2:5], v[182:185], v[230:233], 0
	v_mfma_f32_16x16x32_bf16 v[50:53], v[174:177], v[190:193], 0
	v_mfma_f32_16x16x32_bf16 v[54:57], v[182:185], v[190:193], 0
	v_mfma_f32_16x16x32_bf16 v[38:41], v[178:181], v[218:221], v[38:41]
	v_mfma_f32_16x16x32_bf16 v[34:37], v[186:189], v[218:221], v[34:37]
	v_mfma_f32_16x16x32_bf16 v[22:25], v[178:181], v[226:229], v[22:25]
	v_mfma_f32_16x16x32_bf16 v[18:21], v[186:189], v[226:229], v[18:21]
	v_mfma_f32_16x16x32_bf16 v[6:9], v[178:181], v[234:237], v[6:9]
	v_mfma_f32_16x16x32_bf16 v[2:5], v[186:189], v[234:237], v[2:5]
	v_mfma_f32_16x16x32_bf16 v[50:53], v[178:181], v[194:197], v[50:53]
	v_mfma_f32_16x16x32_bf16 v[54:57], v[186:189], v[194:197], v[54:57]
	s_setprio 0
	s_barrier
	s_add_i32 s51, 0, 0x18000
	v_add_u32_e32 v0, s51, v198
	s_add_i32 s65, 0, 0x1c000
	ds_read_b128 v[58:61], v0
	ds_read_b128 v[62:65], v0 offset:1024
	ds_read_b128 v[66:69], v0 offset:2048
	ds_read_b128 v[70:73], v0 offset:3072
	v_add_u32_e32 v0, s65, v198
	ds_read_b128 v[174:177], v0
	ds_read_b128 v[178:181], v0 offset:1024
	ds_read_b128 v[182:185], v0 offset:2048
	ds_read_b128 v[186:189], v0 offset:3072
	s_add_u32 s48, s48, 0x40000
	s_addc_u32 s49, s49, 0
	s_mov_b32 m0, s54
	v_lshl_add_u64 v[242:243], s[48:49], 0, v[150:151]
	ds_read_b128 v[190:193], v203 offset:32768
	ds_read_b128 v[194:197], v203 offset:33792
	ds_read_b128 v[214:217], v203 offset:34816
	ds_read_b128 v[218:221], v203 offset:35840
	ds_read_b128 v[222:225], v203 offset:36864
	ds_read_b128 v[226:229], v203 offset:37888
	ds_read_b128 v[230:233], v203 offset:38912
	ds_read_b128 v[234:237], v203 offset:39936
	global_load_lds_dwordx4 v[242:243], off
	v_lshl_add_u64 v[242:243], s[48:49], 0, v[154:155]
	s_mov_b32 m0, s55
	s_nop 0
	global_load_lds_dwordx4 v[242:243], off
	s_waitcnt vmcnt(8)
	s_waitcnt lgkmcnt(0)
	s_barrier
	s_setprio 1
	s_waitcnt lgkmcnt(0)
	v_mfma_f32_16x16x32_bf16 v[142:145], v[58:61], v[190:193], v[142:145]
	v_mfma_f32_16x16x32_bf16 v[138:141], v[66:69], v[190:193], v[138:141]
	v_mfma_f32_16x16x32_bf16 v[126:129], v[58:61], v[214:217], v[126:129]
	v_mfma_f32_16x16x32_bf16 v[122:125], v[66:69], v[214:217], v[122:125]
	v_mfma_f32_16x16x32_bf16 v[110:113], v[58:61], v[222:225], v[110:113]
	v_mfma_f32_16x16x32_bf16 v[106:109], v[66:69], v[222:225], v[106:109]
	v_mfma_f32_16x16x32_bf16 v[94:97], v[58:61], v[230:233], v[94:97]
	v_mfma_f32_16x16x32_bf16 v[90:93], v[66:69], v[230:233], v[90:93]
	v_mfma_f32_16x16x32_bf16 v[142:145], v[62:65], v[194:197], v[142:145]
	v_mfma_f32_16x16x32_bf16 v[138:141], v[70:73], v[194:197], v[138:141]
	v_mfma_f32_16x16x32_bf16 v[126:129], v[62:65], v[218:221], v[126:129]
	v_mfma_f32_16x16x32_bf16 v[122:125], v[70:73], v[218:221], v[122:125]
	v_mfma_f32_16x16x32_bf16 v[110:113], v[62:65], v[226:229], v[110:113]
	v_mfma_f32_16x16x32_bf16 v[106:109], v[70:73], v[226:229], v[106:109]
	v_mfma_f32_16x16x32_bf16 v[94:97], v[62:65], v[234:237], v[94:97]
	v_mfma_f32_16x16x32_bf16 v[90:93], v[70:73], v[234:237], v[90:93]
	s_setprio 0
	s_setprio 1
	v_mfma_f32_16x16x32_bf16 v[134:137], v[174:177], v[190:193], v[134:137]
	v_mfma_f32_16x16x32_bf16 v[130:133], v[182:185], v[190:193], v[130:133]
	v_mfma_f32_16x16x32_bf16 v[118:121], v[174:177], v[214:217], v[118:121]
	v_mfma_f32_16x16x32_bf16 v[114:117], v[182:185], v[214:217], v[114:117]
	v_mfma_f32_16x16x32_bf16 v[102:105], v[174:177], v[222:225], v[102:105]
	v_mfma_f32_16x16x32_bf16 v[98:101], v[182:185], v[222:225], v[98:101]
	v_mfma_f32_16x16x32_bf16 v[86:89], v[174:177], v[230:233], v[86:89]
	v_mfma_f32_16x16x32_bf16 v[82:85], v[182:185], v[230:233], v[82:85]
	v_mfma_f32_16x16x32_bf16 v[134:137], v[178:181], v[194:197], v[134:137]
	v_mfma_f32_16x16x32_bf16 v[130:133], v[186:189], v[194:197], v[130:133]
	v_mfma_f32_16x16x32_bf16 v[118:121], v[178:181], v[218:221], v[118:121]
	v_mfma_f32_16x16x32_bf16 v[114:117], v[186:189], v[218:221], v[114:117]
	v_mfma_f32_16x16x32_bf16 v[102:105], v[178:181], v[226:229], v[102:105]
	v_mfma_f32_16x16x32_bf16 v[98:101], v[186:189], v[226:229], v[98:101]
	v_mfma_f32_16x16x32_bf16 v[86:89], v[178:181], v[234:237], v[86:89]
	v_mfma_f32_16x16x32_bf16 v[82:85], v[186:189], v[234:237], v[82:85]
	s_setprio 0
	s_barrier
	s_add_i32 s48, s51, s12
	v_lshl_add_u64 v[166:167], v[166:167], 0, s[14:15]
	s_mov_b32 m0, s48
	ds_read_b128 v[190:193], v203 offset:49152
	ds_read_b128 v[194:197], v203 offset:50176
	ds_read_b128 v[214:217], v203 offset:51200
	ds_read_b128 v[218:221], v203 offset:52224
	ds_read_b128 v[222:225], v203 offset:53248
	ds_read_b128 v[226:229], v203 offset:54272
	ds_read_b128 v[230:233], v203 offset:55296
	ds_read_b128 v[234:237], v203 offset:56320
	global_load_lds_dwordx4 v[166:167], off
	s_add_i32 m0, s48, 0x2000
	s_add_u32 s46, s46, 0x40080
	v_lshl_add_u64 v[166:167], v[204:205], 0, s[14:15]
	s_addc_u32 s47, s47, 0
	s_add_i32 s48, s65, s12
	global_load_lds_dwordx4 v[166:167], off
	v_lshl_add_u64 v[166:167], s[46:47], 0, v[152:153]
	s_mov_b32 m0, s48
	s_nop 0
	global_load_lds_dwordx4 v[166:167], off
	v_lshl_add_u64 v[166:167], s[46:47], 0, v[156:157]
	s_add_i32 m0, s48, 0x2000
	s_nop 0
	global_load_lds_dwordx4 v[166:167], off
	v_lshl_add_u64 v[166:167], v[238:239], 0, s[14:15]
	s_mov_b32 m0, s59
	s_nop 0
	global_load_lds_dwordx4 v[166:167], off
	v_lshl_add_u64 v[166:167], v[240:241], 0, s[14:15]
	s_mov_b32 m0, s60
	s_nop 0
	global_load_lds_dwordx4 v[166:167], off
	s_waitcnt vmcnt(8)
	s_waitcnt lgkmcnt(0)
	s_barrier
	s_setprio 1
	s_waitcnt lgkmcnt(0)
	v_mfma_f32_16x16x32_bf16 v[78:81], v[58:61], v[190:193], v[78:81]
	v_mfma_f32_16x16x32_bf16 v[74:77], v[66:69], v[190:193], v[74:77]
	v_mfma_f32_16x16x32_bf16 v[46:49], v[58:61], v[214:217], v[46:49]
	v_mfma_f32_16x16x32_bf16 v[42:45], v[66:69], v[214:217], v[42:45]
	v_mfma_f32_16x16x32_bf16 v[30:33], v[58:61], v[222:225], v[30:33]
	v_mfma_f32_16x16x32_bf16 v[26:29], v[66:69], v[222:225], v[26:29]
	v_mfma_f32_16x16x32_bf16 v[14:17], v[58:61], v[230:233], v[14:17]
	v_mfma_f32_16x16x32_bf16 v[10:13], v[66:69], v[230:233], v[10:13]
	v_mfma_f32_16x16x32_bf16 v[78:81], v[62:65], v[194:197], v[78:81]
	v_mfma_f32_16x16x32_bf16 v[74:77], v[70:73], v[194:197], v[74:77]
	v_mfma_f32_16x16x32_bf16 v[46:49], v[62:65], v[218:221], v[46:49]
	v_mfma_f32_16x16x32_bf16 v[42:45], v[70:73], v[218:221], v[42:45]
	v_mfma_f32_16x16x32_bf16 v[30:33], v[62:65], v[226:229], v[30:33]
	v_mfma_f32_16x16x32_bf16 v[26:29], v[70:73], v[226:229], v[26:29]
	v_mfma_f32_16x16x32_bf16 v[14:17], v[62:65], v[234:237], v[14:17]
	v_mfma_f32_16x16x32_bf16 v[10:13], v[70:73], v[234:237], v[10:13]
	s_setprio 0
	s_setprio 1
	v_mfma_f32_16x16x32_bf16 v[50:53], v[174:177], v[190:193], v[50:53]
	v_mfma_f32_16x16x32_bf16 v[62:65], v[178:181], v[194:197], v[50:53]
	v_mfma_f32_16x16x32_bf16 v[50:53], v[182:185], v[190:193], v[54:57]
	v_mfma_f32_16x16x32_bf16 v[38:41], v[174:177], v[214:217], v[38:41]
	v_mfma_f32_16x16x32_bf16 v[34:37], v[182:185], v[214:217], v[34:37]
	v_mfma_f32_16x16x32_bf16 v[22:25], v[174:177], v[222:225], v[22:25]
	v_mfma_f32_16x16x32_bf16 v[18:21], v[182:185], v[222:225], v[18:21]
	v_mfma_f32_16x16x32_bf16 v[6:9], v[174:177], v[230:233], v[6:9]
	v_mfma_f32_16x16x32_bf16 v[2:5], v[182:185], v[230:233], v[2:5]
	v_mfma_f32_16x16x32_bf16 v[58:61], v[186:189], v[194:197], v[50:53]
	v_mfma_f32_16x16x32_bf16 v[38:41], v[178:181], v[218:221], v[38:41]
	v_mfma_f32_16x16x32_bf16 v[34:37], v[186:189], v[218:221], v[34:37]
	v_mfma_f32_16x16x32_bf16 v[22:25], v[178:181], v[226:229], v[22:25]
	v_mfma_f32_16x16x32_bf16 v[18:21], v[186:189], v[226:229], v[18:21]
	v_mfma_f32_16x16x32_bf16 v[6:9], v[178:181], v[234:237], v[6:9]
	v_mfma_f32_16x16x32_bf16 v[2:5], v[186:189], v[234:237], v[2:5]
	s_setprio 0
	s_barrier
	s_add_i32 s50, s50, 2
	s_add_u32 s44, s44, 0x100
	s_addc_u32 s45, s45, 0
	s_add_u32 s34, s34, 0x100
	s_addc_u32 s43, s43, 0
	s_cmp_gt_u32 s50, 13
	s_cbranch_scc1 .Lpeel_k511_exit

.Lpeel_k511_exit:
	s_and_b64 vcc, exec, s[8:9]
	s_cbranch_vccz .LBB0_514
	s_barrier

.LBB0_1066:
	s_ashr_i32 s23, s22, 31
	s_lshl_b64 s[26:27], s[22:23], 19
	s_add_u32 s30, s16, s26
	s_addc_u32 s31, s52, s27
	s_and_b64 s[26:27], s[36:37], exec
	s_cselect_b32 s21, s31, s45
	s_cselect_b32 s23, s30, s44
	s_ashr_i32 s19, s18, 31
	s_lshl_b64 s[26:27], s[18:19], 19
	s_add_u32 s40, s53, s26
	s_addc_u32 s41, s54, s27
	s_and_b64 s[26:27], s[36:37], exec
	s_cselect_b32 s19, s41, s47
	s_cselect_b32 s26, s40, s46
	s_add_u32 s44, s44, 0x40080
	s_addc_u32 s45, s45, 0
	s_add_u32 s27, s46, 0x100
	v_mov_b32_e32 v2, 0
	s_addc_u32 s29, s47, 0
	s_mov_b32 s34, -2
	s_cmp_eq_u32 s20, 0
	s_cbranch_scc1 .Ltb_hg_skip
	s_cmp_eq_u32 s4, 0
	s_cbranch_scc1 .Ltb_hg_skip
	s_barrier
.Ltb_hg_skip:
	s_add_u32 s39, s44, 0xfffc0080
	s_addc_u32 s43, s45, -1
	s_add_i32 s50, 0, 0x10000
	s_cmp_eq_u32 s34, 12
	s_cselect_b32 s49, s21, s43
	s_cselect_b32 s48, s23, s39
	s_cselect_b32 s47, s19, s29
	s_cselect_b32 s46, s26, s27
	s_add_i32 s39, 0, 0x14000
	v_add_u32_e32 v142, s50, v222
	v_add_u32_e32 v166, s39, v222
	ds_read_b128 v[130:133], v142
	ds_read_b128 v[134:137], v142 offset:1024
	ds_read_b128 v[138:141], v142 offset:2048
	ds_read_b128 v[142:145], v142 offset:3072
	s_waitcnt lgkmcnt(0)
	ds_read_b128 v[174:177], v166
	ds_read_b128 v[178:181], v166 offset:1024
	ds_read_b128 v[182:185], v166 offset:2048
	ds_read_b128 v[186:189], v166 offset:3072
	v_lshl_add_u64 v[244:245], s[44:45], 0, v[162:163]
	s_add_i32 m0, s55, 0xc000
	ds_read_b128 v[190:193], v157
	ds_read_b128 v[194:197], v157 offset:1024
	ds_read_b128 v[198:201], v157 offset:2048
	ds_read_b128 v[202:205], v157 offset:3072
	ds_read_b128 v[228:231], v157 offset:4096
	ds_read_b128 v[232:235], v157 offset:5120
	ds_read_b128 v[236:239], v157 offset:6144
	ds_read_b128 v[240:243], v157 offset:7168
	global_load_lds_dwordx4 v[244:245], off
	v_lshl_add_u64 v[244:245], s[44:45], 0, v[164:165]
	s_add_i32 m0, s55, 0xe000
	s_nop 0
	global_load_lds_dwordx4 v[244:245], off
	s_waitcnt vmcnt(8)
	s_waitcnt lgkmcnt(0)
	s_barrier
	s_setprio 1
	s_waitcnt lgkmcnt(0)
	v_mfma_f32_16x16x32_bf16 v[126:129], v[130:133], v[190:193], 0
	v_mfma_f32_16x16x32_bf16 v[122:125], v[138:141], v[190:193], 0
	v_mfma_f32_16x16x32_bf16 v[110:113], v[130:133], v[198:201], 0
	v_mfma_f32_16x16x32_bf16 v[106:109], v[138:141], v[198:201], 0
	v_mfma_f32_16x16x32_bf16 v[94:97], v[130:133], v[228:231], 0
	v_mfma_f32_16x16x32_bf16 v[90:93], v[138:141], v[228:231], 0
	v_mfma_f32_16x16x32_bf16 v[78:81], v[130:133], v[236:239], 0
	v_mfma_f32_16x16x32_bf16 v[74:77], v[138:141], v[236:239], 0
	v_mfma_f32_16x16x32_bf16 v[126:129], v[134:137], v[194:197], v[126:129]
	v_mfma_f32_16x16x32_bf16 v[122:125], v[142:145], v[194:197], v[122:125]
	v_mfma_f32_16x16x32_bf16 v[110:113], v[134:137], v[202:205], v[110:113]
	v_mfma_f32_16x16x32_bf16 v[106:109], v[142:145], v[202:205], v[106:109]
	v_mfma_f32_16x16x32_bf16 v[94:97], v[134:137], v[232:235], v[94:97]
	v_mfma_f32_16x16x32_bf16 v[90:93], v[142:145], v[232:235], v[90:93]
	v_mfma_f32_16x16x32_bf16 v[78:81], v[134:137], v[240:243], v[78:81]
	v_mfma_f32_16x16x32_bf16 v[74:77], v[142:145], v[240:243], v[74:77]
	s_setprio 0
	s_setprio 1
	v_mfma_f32_16x16x32_bf16 v[118:121], v[174:177], v[190:193], 0
	v_mfma_f32_16x16x32_bf16 v[114:117], v[182:185], v[190:193], 0
	v_mfma_f32_16x16x32_bf16 v[102:105], v[174:177], v[198:201], 0
	v_mfma_f32_16x16x32_bf16 v[98:101], v[182:185], v[198:201], 0
	v_mfma_f32_16x16x32_bf16 v[86:89], v[174:177], v[228:231], 0
	v_mfma_f32_16x16x32_bf16 v[82:85], v[182:185], v[228:231], 0
	v_mfma_f32_16x16x32_bf16 v[70:73], v[174:177], v[236:239], 0
	v_mfma_f32_16x16x32_bf16 v[66:69], v[182:185], v[236:239], 0
	v_mfma_f32_16x16x32_bf16 v[118:121], v[178:181], v[194:197], v[118:121]
	v_mfma_f32_16x16x32_bf16 v[114:117], v[186:189], v[194:197], v[114:117]
	v_mfma_f32_16x16x32_bf16 v[102:105], v[178:181], v[202:205], v[102:105]
	v_mfma_f32_16x16x32_bf16 v[98:101], v[186:189], v[202:205], v[98:101]
	v_mfma_f32_16x16x32_bf16 v[86:89], v[178:181], v[232:235], v[86:89]
	v_mfma_f32_16x16x32_bf16 v[82:85], v[186:189], v[232:235], v[82:85]
	v_mfma_f32_16x16x32_bf16 v[70:73], v[178:181], v[240:243], v[70:73]
	v_mfma_f32_16x16x32_bf16 v[66:69], v[186:189], v[240:243], v[66:69]
	s_setprio 0
	s_barrier
	s_add_i32 s43, s50, s13
	v_lshl_add_u64 v[244:245], s[46:47], 0, v[0:1]
	s_mov_b32 m0, s43
	ds_read_b128 v[190:193], v157 offset:16384
	ds_read_b128 v[194:197], v157 offset:17408
	ds_read_b128 v[198:201], v157 offset:18432
	ds_read_b128 v[202:205], v157 offset:19456
	ds_read_b128 v[228:231], v157 offset:20480
	ds_read_b128 v[232:235], v157 offset:21504
	ds_read_b128 v[236:239], v157 offset:22528
	ds_read_b128 v[240:243], v157 offset:23552
	global_load_lds_dwordx4 v[244:245], off
	s_add_i32 m0, s43, 0x2000
	s_add_u32 s50, s46, 0x40000
	v_lshl_add_u64 v[246:247], s[46:47], 0, v[154:155]
	s_addc_u32 s51, s47, 0
	s_add_i32 s39, s39, s13
	global_load_lds_dwordx4 v[246:247], off
	v_lshl_add_u64 v[248:249], s[50:51], 0, v[0:1]
	s_mov_b32 m0, s39
	v_lshl_add_u64 v[250:251], s[48:49], 0, v[152:153]
	global_load_lds_dwordx4 v[248:249], off
	v_lshl_add_u64 v[248:249], s[50:51], 0, v[154:155]
	s_add_i32 m0, s39, 0x2000
	s_nop 0
	global_load_lds_dwordx4 v[248:249], off
	v_lshl_add_u64 v[248:249], s[48:49], 0, v[150:151]
	s_mov_b32 m0, s55
	s_nop 0
	global_load_lds_dwordx4 v[248:249], off
	s_mov_b32 m0, s56
	s_nop 0
	global_load_lds_dwordx4 v[250:251], off
	s_waitcnt vmcnt(8)
	s_waitcnt lgkmcnt(0)
	s_barrier
	s_setprio 1
	s_waitcnt lgkmcnt(0)
	v_mfma_f32_16x16x32_bf16 v[62:65], v[130:133], v[190:193], 0
	v_mfma_f32_16x16x32_bf16 v[58:61], v[138:141], v[190:193], 0
	v_mfma_f32_16x16x32_bf16 v[46:49], v[130:133], v[198:201], 0
	v_mfma_f32_16x16x32_bf16 v[42:45], v[138:141], v[198:201], 0
	v_mfma_f32_16x16x32_bf16 v[30:33], v[130:133], v[228:231], 0
	v_mfma_f32_16x16x32_bf16 v[26:29], v[138:141], v[228:231], 0
	v_mfma_f32_16x16x32_bf16 v[14:17], v[130:133], v[236:239], 0
	v_mfma_f32_16x16x32_bf16 v[10:13], v[138:141], v[236:239], 0
	v_mfma_f32_16x16x32_bf16 v[62:65], v[134:137], v[194:197], v[62:65]
	v_mfma_f32_16x16x32_bf16 v[58:61], v[142:145], v[194:197], v[58:61]
	v_mfma_f32_16x16x32_bf16 v[46:49], v[134:137], v[202:205], v[46:49]
	v_mfma_f32_16x16x32_bf16 v[42:45], v[142:145], v[202:205], v[42:45]
	v_mfma_f32_16x16x32_bf16 v[30:33], v[134:137], v[232:235], v[30:33]
	v_mfma_f32_16x16x32_bf16 v[26:29], v[142:145], v[232:235], v[26:29]
	v_mfma_f32_16x16x32_bf16 v[14:17], v[134:137], v[240:243], v[14:17]
	v_mfma_f32_16x16x32_bf16 v[10:13], v[142:145], v[240:243], v[10:13]
	s_setprio 0
	s_setprio 1
	v_mfma_f32_16x16x32_bf16 v[54:57], v[174:177], v[190:193], 0
	v_mfma_f32_16x16x32_bf16 v[50:53], v[182:185], v[190:193], 0
	v_mfma_f32_16x16x32_bf16 v[38:41], v[174:177], v[198:201], 0
	v_mfma_f32_16x16x32_bf16 v[34:37], v[182:185], v[198:201], 0
	v_mfma_f32_16x16x32_bf16 v[22:25], v[174:177], v[228:231], 0
	v_mfma_f32_16x16x32_bf16 v[18:21], v[182:185], v[228:231], 0
	v_mfma_f32_16x16x32_bf16 v[6:9], v[174:177], v[236:239], 0
	v_mfma_f32_16x16x32_bf16 v[2:5], v[182:185], v[236:239], 0
	v_mfma_f32_16x16x32_bf16 v[54:57], v[178:181], v[194:197], v[54:57]
	v_mfma_f32_16x16x32_bf16 v[50:53], v[186:189], v[194:197], v[50:53]
	v_mfma_f32_16x16x32_bf16 v[38:41], v[178:181], v[202:205], v[38:41]
	v_mfma_f32_16x16x32_bf16 v[34:37], v[186:189], v[202:205], v[34:37]
	v_mfma_f32_16x16x32_bf16 v[22:25], v[178:181], v[232:235], v[22:25]
	v_mfma_f32_16x16x32_bf16 v[18:21], v[186:189], v[232:235], v[18:21]
	v_mfma_f32_16x16x32_bf16 v[6:9], v[178:181], v[240:243], v[6:9]
	v_mfma_f32_16x16x32_bf16 v[2:5], v[186:189], v[240:243], v[2:5]
	s_setprio 0
	s_barrier
	s_add_i32 s39, 0, 0x18000
	s_add_i32 s43, 0, 0x1c000
	v_add_u32_e32 v142, s39, v222
	v_add_u32_e32 v166, s43, v222
	ds_read_b128 v[130:133], v142
	ds_read_b128 v[134:137], v142 offset:1024
	ds_read_b128 v[138:141], v142 offset:2048
	ds_read_b128 v[142:145], v142 offset:3072
	ds_read_b128 v[174:177], v166
	ds_read_b128 v[178:181], v166 offset:1024
	ds_read_b128 v[182:185], v166 offset:2048
	ds_read_b128 v[186:189], v166 offset:3072
	s_add_u32 s48, s48, 0x40000
	s_addc_u32 s49, s49, 0
	s_mov_b32 m0, s57
	v_lshl_add_u64 v[166:167], s[48:49], 0, v[150:151]
	ds_read_b128 v[190:193], v157 offset:32768
	ds_read_b128 v[194:197], v157 offset:33792
	ds_read_b128 v[198:201], v157 offset:34816
	ds_read_b128 v[202:205], v157 offset:35840
	ds_read_b128 v[228:231], v157 offset:36864
	ds_read_b128 v[232:235], v157 offset:37888
	ds_read_b128 v[236:239], v157 offset:38912
	ds_read_b128 v[240:243], v157 offset:39936
	global_load_lds_dwordx4 v[166:167], off
	v_lshl_add_u64 v[166:167], s[48:49], 0, v[152:153]
	s_mov_b32 m0, s58
	s_nop 0
	global_load_lds_dwordx4 v[166:167], off
	s_waitcnt vmcnt(8)
	s_waitcnt lgkmcnt(0)
	s_barrier
	s_setprio 1
	s_waitcnt lgkmcnt(0)
	v_mfma_f32_16x16x32_bf16 v[126:129], v[130:133], v[190:193], v[126:129]
	v_mfma_f32_16x16x32_bf16 v[122:125], v[138:141], v[190:193], v[122:125]
	v_mfma_f32_16x16x32_bf16 v[110:113], v[130:133], v[198:201], v[110:113]
	v_mfma_f32_16x16x32_bf16 v[106:109], v[138:141], v[198:201], v[106:109]
	v_mfma_f32_16x16x32_bf16 v[94:97], v[130:133], v[228:231], v[94:97]
	v_mfma_f32_16x16x32_bf16 v[90:93], v[138:141], v[228:231], v[90:93]
	v_mfma_f32_16x16x32_bf16 v[78:81], v[130:133], v[236:239], v[78:81]
	v_mfma_f32_16x16x32_bf16 v[74:77], v[138:141], v[236:239], v[74:77]
	v_mfma_f32_16x16x32_bf16 v[126:129], v[134:137], v[194:197], v[126:129]
	v_mfma_f32_16x16x32_bf16 v[122:125], v[142:145], v[194:197], v[122:125]
	v_mfma_f32_16x16x32_bf16 v[110:113], v[134:137], v[202:205], v[110:113]
	v_mfma_f32_16x16x32_bf16 v[106:109], v[142:145], v[202:205], v[106:109]
	v_mfma_f32_16x16x32_bf16 v[94:97], v[134:137], v[232:235], v[94:97]
	v_mfma_f32_16x16x32_bf16 v[90:93], v[142:145], v[232:235], v[90:93]
	v_mfma_f32_16x16x32_bf16 v[78:81], v[134:137], v[240:243], v[78:81]
	v_mfma_f32_16x16x32_bf16 v[74:77], v[142:145], v[240:243], v[74:77]
	s_setprio 0
	s_setprio 1
	v_mfma_f32_16x16x32_bf16 v[118:121], v[174:177], v[190:193], v[118:121]
	v_mfma_f32_16x16x32_bf16 v[114:117], v[182:185], v[190:193], v[114:117]
	v_mfma_f32_16x16x32_bf16 v[102:105], v[174:177], v[198:201], v[102:105]
	v_mfma_f32_16x16x32_bf16 v[98:101], v[182:185], v[198:201], v[98:101]
	v_mfma_f32_16x16x32_bf16 v[86:89], v[174:177], v[228:231], v[86:89]
	v_mfma_f32_16x16x32_bf16 v[82:85], v[182:185], v[228:231], v[82:85]
	v_mfma_f32_16x16x32_bf16 v[70:73], v[174:177], v[236:239], v[70:73]
	v_mfma_f32_16x16x32_bf16 v[66:69], v[182:185], v[236:239], v[66:69]
	v_mfma_f32_16x16x32_bf16 v[118:121], v[178:181], v[194:197], v[118:121]
	v_mfma_f32_16x16x32_bf16 v[114:117], v[186:189], v[194:197], v[114:117]
	v_mfma_f32_16x16x32_bf16 v[102:105], v[178:181], v[202:205], v[102:105]
	v_mfma_f32_16x16x32_bf16 v[98:101], v[186:189], v[202:205], v[98:101]
	v_mfma_f32_16x16x32_bf16 v[86:89], v[178:181], v[232:235], v[86:89]
	v_mfma_f32_16x16x32_bf16 v[82:85], v[186:189], v[232:235], v[82:85]
	v_mfma_f32_16x16x32_bf16 v[70:73], v[178:181], v[240:243], v[70:73]
	v_mfma_f32_16x16x32_bf16 v[66:69], v[186:189], v[240:243], v[66:69]
	s_setprio 0
	s_barrier
	s_add_i32 s39, s39, s13
	v_lshl_add_u64 v[166:167], v[244:245], 0, s[14:15]
	s_mov_b32 m0, s39
	ds_read_b128 v[190:193], v157 offset:49152
	ds_read_b128 v[194:197], v157 offset:50176
	ds_read_b128 v[198:201], v157 offset:51200
	ds_read_b128 v[202:205], v157 offset:52224
	ds_read_b128 v[228:231], v157 offset:53248
	ds_read_b128 v[232:235], v157 offset:54272
	ds_read_b128 v[236:239], v157 offset:55296
	ds_read_b128 v[240:243], v157 offset:56320
	global_load_lds_dwordx4 v[166:167], off
	s_add_i32 m0, s39, 0x2000
	s_add_u32 s46, s46, 0x40080
	v_lshl_add_u64 v[166:167], v[246:247], 0, s[14:15]
	s_addc_u32 s47, s47, 0
	s_add_i32 s39, s43, s13
	global_load_lds_dwordx4 v[166:167], off
	v_lshl_add_u64 v[166:167], s[46:47], 0, v[0:1]
	s_mov_b32 m0, s39
	s_nop 0
	global_load_lds_dwordx4 v[166:167], off
	v_lshl_add_u64 v[166:167], s[46:47], 0, v[154:155]
	s_add_i32 m0, s39, 0x2000
	s_nop 0
	global_load_lds_dwordx4 v[166:167], off
	v_lshl_add_u64 v[166:167], v[248:249], 0, s[14:15]
	s_mov_b32 m0, s61
	s_nop 0
	global_load_lds_dwordx4 v[166:167], off
	v_lshl_add_u64 v[166:167], v[250:251], 0, s[14:15]
	s_mov_b32 m0, s62
	s_nop 0
	global_load_lds_dwordx4 v[166:167], off
	s_waitcnt vmcnt(8)
	s_waitcnt lgkmcnt(0)
	s_barrier
	s_setprio 1
	s_waitcnt lgkmcnt(0)
	v_mfma_f32_16x16x32_bf16 v[62:65], v[130:133], v[190:193], v[62:65]
	v_mfma_f32_16x16x32_bf16 v[58:61], v[138:141], v[190:193], v[58:61]
	v_mfma_f32_16x16x32_bf16 v[46:49], v[130:133], v[198:201], v[46:49]
	v_mfma_f32_16x16x32_bf16 v[42:45], v[138:141], v[198:201], v[42:45]
	v_mfma_f32_16x16x32_bf16 v[30:33], v[130:133], v[228:231], v[30:33]
	v_mfma_f32_16x16x32_bf16 v[26:29], v[138:141], v[228:231], v[26:29]
	v_mfma_f32_16x16x32_bf16 v[14:17], v[130:133], v[236:239], v[14:17]
	v_mfma_f32_16x16x32_bf16 v[10:13], v[138:141], v[236:239], v[10:13]
	v_mfma_f32_16x16x32_bf16 v[62:65], v[134:137], v[194:197], v[62:65]
	v_mfma_f32_16x16x32_bf16 v[58:61], v[142:145], v[194:197], v[58:61]
	v_mfma_f32_16x16x32_bf16 v[46:49], v[134:137], v[202:205], v[46:49]
	v_mfma_f32_16x16x32_bf16 v[42:45], v[142:145], v[202:205], v[42:45]
	v_mfma_f32_16x16x32_bf16 v[30:33], v[134:137], v[232:235], v[30:33]
	v_mfma_f32_16x16x32_bf16 v[26:29], v[142:145], v[232:235], v[26:29]
	v_mfma_f32_16x16x32_bf16 v[14:17], v[134:137], v[240:243], v[14:17]
	v_mfma_f32_16x16x32_bf16 v[10:13], v[142:145], v[240:243], v[10:13]
	s_setprio 0
	s_setprio 1
	v_mfma_f32_16x16x32_bf16 v[54:57], v[174:177], v[190:193], v[54:57]
	v_mfma_f32_16x16x32_bf16 v[50:53], v[182:185], v[190:193], v[50:53]
	v_mfma_f32_16x16x32_bf16 v[38:41], v[174:177], v[198:201], v[38:41]
	v_mfma_f32_16x16x32_bf16 v[34:37], v[182:185], v[198:201], v[34:37]
	v_mfma_f32_16x16x32_bf16 v[22:25], v[174:177], v[228:231], v[22:25]
	v_mfma_f32_16x16x32_bf16 v[18:21], v[182:185], v[228:231], v[18:21]
	v_mfma_f32_16x16x32_bf16 v[6:9], v[174:177], v[236:239], v[6:9]
	v_mfma_f32_16x16x32_bf16 v[2:5], v[182:185], v[236:239], v[2:5]
	v_mfma_f32_16x16x32_bf16 v[54:57], v[178:181], v[194:197], v[54:57]
	v_mfma_f32_16x16x32_bf16 v[50:53], v[186:189], v[194:197], v[50:53]
	v_mfma_f32_16x16x32_bf16 v[38:41], v[178:181], v[202:205], v[38:41]
	v_mfma_f32_16x16x32_bf16 v[34:37], v[186:189], v[202:205], v[34:37]
	v_mfma_f32_16x16x32_bf16 v[22:25], v[178:181], v[232:235], v[22:25]
	v_mfma_f32_16x16x32_bf16 v[18:21], v[186:189], v[232:235], v[18:21]
	v_mfma_f32_16x16x32_bf16 v[6:9], v[178:181], v[240:243], v[6:9]
	v_mfma_f32_16x16x32_bf16 v[2:5], v[186:189], v[240:243], v[2:5]
	s_setprio 0
	s_barrier
	s_add_i32 s34, s34, 2
	s_add_u32 s44, s44, 0x100
	s_addc_u32 s45, s45, 0
	s_add_u32 s27, s27, 0x100
	s_addc_u32 s29, s29, 0
	s_cmp_gt_u32 s34, 13
	s_cbranch_scc1 .Lpeel_k1067_exit

.LBB0_1381:
	v_bfe_u32 v181, v170, 4, 2
	v_and_b32_e32 v18, 15, v170
	v_lshlrev_b32_e32 v19, 4, v181
	v_lshl_or_b32 v132, s8, 6, v18
	v_lshl_or_b32 v18, v18, 6, v19
	v_lshlrev_b32_e32 v19, 2, v170
	s_and_b32 s13, s7, 3
	s_lshl_b32 s7, s8, 13
	v_and_b32_e32 v19, 32, v19
	s_add_i32 m0, s20, 0x18000
	v_lshl_add_u64 v[8:9], v[8:9], 0, s[14:15]
	v_bitop3_b32 v20, v18, s7, v19 bitop3:0xde
	s_lshl_b32 s7, s13, 12
	s_waitcnt vmcnt(2)
	s_barrier
	global_load_lds_dwordx4 v[8:9], off
	v_lshl_add_u64 v[6:7], v[6:7], 0, s[14:15]
	s_add_i32 m0, s20, 0x1a000
	s_add_i32 s24, s20, 0x8000
	s_add_i32 s25, s20, 0xa000
	global_load_lds_dwordx4 v[6:7], off
	v_lshl_add_u64 v[4:5], v[4:5], 0, s[14:15]
	s_mov_b32 m0, s24
	s_add_u32 s8, s2, 0xb0080
	global_load_lds_dwordx4 v[4:5], off
	v_lshl_add_u64 v[2:3], v[2:3], 0, s[14:15]
	s_mov_b32 m0, s25
	s_addc_u32 s9, s3, 0
	global_load_lds_dwordx4 v[2:3], off
	s_add_i32 m0, s20, 0x1c000
	v_lshl_add_u64 v[2:3], s[8:9], 0, v[0:1]
	global_load_lds_dwordx4 v[2:3], off
	v_lshl_add_u64 v[2:3], s[8:9], 0, v[126:127]
	s_add_i32 m0, s20, 0x1e000
	s_movk_i32 s10, 0xb00
	global_load_lds_dwordx4 v[2:3], off
	v_lshrrev_b32_e32 v3, 1, v10
	v_mul_lo_u32 v2, v12, s10
	s_mov_b32 s11, 0xb000
	v_bitop3_b32 v133, s7, v18, v19 bitop3:0xf6
	s_mul_hi_u32 s8, s6, 0x160000
	s_mul_i32 s9, s6, 0x160000
	v_mad_u64_u32 v[2:3], s[6:7], v3, s11, v[2:3]
	v_or_b32_e32 v2, v2, v11
	s_add_u32 s6, s70, s9
	v_add_lshl_u32 v2, v2, v13, 1
	v_mov_b32_e32 v3, v1
	s_addc_u32 s7, s71, s8
	v_lshl_add_u64 v[128:129], s[6:7], 0, v[2:3]
	v_lshrrev_b32_e32 v3, 1, v14
	v_mul_lo_u32 v2, v16, s10
	v_mad_u64_u32 v[2:3], s[8:9], v3, s11, v[2:3]
	v_or_b32_e32 v2, v2, v15
	s_waitcnt vmcnt(6)
	v_add_lshl_u32 v2, v2, v17, 1
	v_mov_b32_e32 v3, v1
	v_lshl_add_u64 v[130:131], s[6:7], 0, v[2:3]
	v_mov_b32_e32 v2, 0
	s_mov_b32 s26, -2
	s_mov_b64 s[6:7], 0x14eb0080
	v_add_u32_e32 v142, 0, v20
	s_barrier
	s_add_u32 s8, s6, 0xeb150080
	s_addc_u32 s9, s7, -1
	s_cmp_lg_u32 s26, 40
	s_cselect_b32 s8, s8, 0
	s_cselect_b32 s9, s9, 0
	s_add_u32 s10, s4, s8
	s_addc_u32 s11, s5, s9
	s_add_i32 s27, 0, 0x10000
	s_add_u32 s8, s2, s8
	v_add_u32_e32 v143, s27, v133
	s_addc_u32 s9, s3, s9
	s_add_i32 s29, 0, 0x14000
	ds_read_b128 v[150:153], v143
	ds_read_b128 v[154:157], v143 offset:1024
	ds_read_b128 v[158:161], v143 offset:2048
	ds_read_b128 v[162:165], v143 offset:3072
	v_add_u32_e32 v143, s29, v133
	ds_read_b128 v[170:173], v143
	ds_read_b128 v[174:177], v143 offset:1024
	ds_read_b128 v[182:185], v143 offset:2048
	ds_read_b128 v[186:189], v143 offset:3072
	v_lshl_add_u64 v[144:145], v[128:129], 0, s[6:7]
	s_add_i32 m0, s20, 0xc000
	ds_read_b128 v[190:193], v142
	ds_read_b128 v[194:197], v142 offset:1024
	ds_read_b128 v[198:201], v142 offset:2048
	ds_read_b128 v[202:205], v142 offset:3072
	ds_read_b128 v[214:217], v142 offset:4096
	ds_read_b128 v[218:221], v142 offset:5120
	ds_read_b128 v[222:225], v142 offset:6144
	ds_read_b128 v[226:229], v142 offset:7168
	global_load_lds_dwordx4 v[144:145], off
	v_lshl_add_u64 v[144:145], v[130:131], 0, s[6:7]
	s_add_i32 m0, s20, 0xe000
	s_nop 0
	global_load_lds_dwordx4 v[144:145], off
	s_waitcnt vmcnt(8)
	s_waitcnt lgkmcnt(0)
	s_barrier
	s_setprio 1
	s_waitcnt lgkmcnt(0)
	v_mfma_f32_16x16x32_bf16 v[138:141], v[150:153], v[190:193], 0
	v_mfma_f32_16x16x32_bf16 v[134:137], v[158:161], v[190:193], 0
	v_mfma_f32_16x16x32_bf16 v[110:113], v[150:153], v[198:201], 0
	v_mfma_f32_16x16x32_bf16 v[106:109], v[158:161], v[198:201], 0
	v_mfma_f32_16x16x32_bf16 v[94:97], v[150:153], v[214:217], 0
	v_mfma_f32_16x16x32_bf16 v[90:93], v[158:161], v[214:217], 0
	v_mfma_f32_16x16x32_bf16 v[78:81], v[150:153], v[222:225], 0
	v_mfma_f32_16x16x32_bf16 v[74:77], v[158:161], v[222:225], 0
	v_mfma_f32_16x16x32_bf16 v[138:141], v[154:157], v[194:197], v[138:141]
	v_mfma_f32_16x16x32_bf16 v[134:137], v[162:165], v[194:197], v[134:137]
	v_mfma_f32_16x16x32_bf16 v[110:113], v[154:157], v[202:205], v[110:113]
	v_mfma_f32_16x16x32_bf16 v[106:109], v[162:165], v[202:205], v[106:109]
	v_mfma_f32_16x16x32_bf16 v[94:97], v[154:157], v[218:221], v[94:97]
	v_mfma_f32_16x16x32_bf16 v[90:93], v[162:165], v[218:221], v[90:93]
	v_mfma_f32_16x16x32_bf16 v[78:81], v[154:157], v[226:229], v[78:81]
	v_mfma_f32_16x16x32_bf16 v[74:77], v[162:165], v[226:229], v[74:77]
	s_setprio 0
	s_setprio 1
	v_mfma_f32_16x16x32_bf16 v[122:125], v[170:173], v[190:193], 0
	v_mfma_f32_16x16x32_bf16 v[114:117], v[182:185], v[190:193], 0
	v_mfma_f32_16x16x32_bf16 v[102:105], v[170:173], v[198:201], 0
	v_mfma_f32_16x16x32_bf16 v[98:101], v[182:185], v[198:201], 0
	v_mfma_f32_16x16x32_bf16 v[86:89], v[170:173], v[214:217], 0
	v_mfma_f32_16x16x32_bf16 v[82:85], v[182:185], v[214:217], 0
	v_mfma_f32_16x16x32_bf16 v[70:73], v[170:173], v[222:225], 0
	v_mfma_f32_16x16x32_bf16 v[66:69], v[182:185], v[222:225], 0
	v_mfma_f32_16x16x32_bf16 v[122:125], v[174:177], v[194:197], v[122:125]
	v_mfma_f32_16x16x32_bf16 v[114:117], v[186:189], v[194:197], v[114:117]
	v_mfma_f32_16x16x32_bf16 v[102:105], v[174:177], v[202:205], v[102:105]
	v_mfma_f32_16x16x32_bf16 v[98:101], v[186:189], v[202:205], v[98:101]
	v_mfma_f32_16x16x32_bf16 v[86:89], v[174:177], v[218:221], v[86:89]
	v_mfma_f32_16x16x32_bf16 v[82:85], v[186:189], v[218:221], v[82:85]
	v_mfma_f32_16x16x32_bf16 v[70:73], v[174:177], v[226:229], v[70:73]
	v_mfma_f32_16x16x32_bf16 v[66:69], v[186:189], v[226:229], v[66:69]
	s_setprio 0
	s_barrier
	s_add_i32 s27, s27, s19
	v_lshl_add_u64 v[144:145], s[8:9], 0, v[0:1]
	s_mov_b32 m0, s27
	ds_read_b128 v[190:193], v142 offset:16384
	ds_read_b128 v[194:197], v142 offset:17408
	ds_read_b128 v[198:201], v142 offset:18432
	ds_read_b128 v[202:205], v142 offset:19456
	ds_read_b128 v[214:217], v142 offset:20480
	ds_read_b128 v[218:221], v142 offset:21504
	ds_read_b128 v[222:225], v142 offset:22528
	ds_read_b128 v[226:229], v142 offset:23552
	global_load_lds_dwordx4 v[144:145], off
	s_add_i32 m0, s27, 0x2000
	s_add_u32 s30, s8, 0xb0000
	v_lshl_add_u64 v[166:167], s[8:9], 0, v[126:127]
	s_addc_u32 s31, s9, 0
	s_add_i32 s27, s29, s19
	global_load_lds_dwordx4 v[166:167], off
	v_lshl_add_u64 v[178:179], s[30:31], 0, v[0:1]
	s_mov_b32 m0, s27
	v_lshl_add_u64 v[230:231], s[10:11], 0, v[120:121]
	global_load_lds_dwordx4 v[178:179], off
	v_lshl_add_u64 v[178:179], s[30:31], 0, v[126:127]
	s_add_i32 m0, s27, 0x2000
	s_nop 0
	global_load_lds_dwordx4 v[178:179], off
	v_lshl_add_u64 v[178:179], s[10:11], 0, v[118:119]
	s_mov_b32 m0, s20
	s_nop 0
	global_load_lds_dwordx4 v[178:179], off
	s_mov_b32 m0, s21
	s_nop 0
	global_load_lds_dwordx4 v[230:231], off
	s_waitcnt vmcnt(8)
	s_waitcnt lgkmcnt(0)
	s_barrier
	s_setprio 1
	s_waitcnt lgkmcnt(0)
	v_mfma_f32_16x16x32_bf16 v[62:65], v[150:153], v[190:193], 0
	v_mfma_f32_16x16x32_bf16 v[58:61], v[158:161], v[190:193], 0
	v_mfma_f32_16x16x32_bf16 v[46:49], v[150:153], v[198:201], 0
	v_mfma_f32_16x16x32_bf16 v[42:45], v[158:161], v[198:201], 0
	v_mfma_f32_16x16x32_bf16 v[30:33], v[150:153], v[214:217], 0
	v_mfma_f32_16x16x32_bf16 v[26:29], v[158:161], v[214:217], 0
	v_mfma_f32_16x16x32_bf16 v[14:17], v[150:153], v[222:225], 0
	v_mfma_f32_16x16x32_bf16 v[10:13], v[158:161], v[222:225], 0
	v_mfma_f32_16x16x32_bf16 v[62:65], v[154:157], v[194:197], v[62:65]
	v_mfma_f32_16x16x32_bf16 v[58:61], v[162:165], v[194:197], v[58:61]
	v_mfma_f32_16x16x32_bf16 v[46:49], v[154:157], v[202:205], v[46:49]
	v_mfma_f32_16x16x32_bf16 v[42:45], v[162:165], v[202:205], v[42:45]
	v_mfma_f32_16x16x32_bf16 v[30:33], v[154:157], v[218:221], v[30:33]
	v_mfma_f32_16x16x32_bf16 v[26:29], v[162:165], v[218:221], v[26:29]
	v_mfma_f32_16x16x32_bf16 v[14:17], v[154:157], v[226:229], v[14:17]
	v_mfma_f32_16x16x32_bf16 v[10:13], v[162:165], v[226:229], v[10:13]
	s_setprio 0
	s_setprio 1
	v_mfma_f32_16x16x32_bf16 v[54:57], v[170:173], v[190:193], 0
	v_mfma_f32_16x16x32_bf16 v[50:53], v[182:185], v[190:193], 0
	v_mfma_f32_16x16x32_bf16 v[38:41], v[170:173], v[198:201], 0
	v_mfma_f32_16x16x32_bf16 v[34:37], v[182:185], v[198:201], 0
	v_mfma_f32_16x16x32_bf16 v[22:25], v[170:173], v[214:217], 0
	v_mfma_f32_16x16x32_bf16 v[18:21], v[182:185], v[214:217], 0
	v_mfma_f32_16x16x32_bf16 v[6:9], v[170:173], v[222:225], 0
	v_mfma_f32_16x16x32_bf16 v[2:5], v[182:185], v[222:225], 0
	v_mfma_f32_16x16x32_bf16 v[54:57], v[174:177], v[194:197], v[54:57]
	v_mfma_f32_16x16x32_bf16 v[50:53], v[186:189], v[194:197], v[50:53]
	v_mfma_f32_16x16x32_bf16 v[38:41], v[174:177], v[202:205], v[38:41]
	v_mfma_f32_16x16x32_bf16 v[34:37], v[186:189], v[202:205], v[34:37]
	v_mfma_f32_16x16x32_bf16 v[22:25], v[174:177], v[218:221], v[22:25]
	v_mfma_f32_16x16x32_bf16 v[18:21], v[186:189], v[218:221], v[18:21]
	v_mfma_f32_16x16x32_bf16 v[6:9], v[174:177], v[226:229], v[6:9]
	v_mfma_f32_16x16x32_bf16 v[2:5], v[186:189], v[226:229], v[2:5]
	s_setprio 0
	s_barrier
	s_add_i32 s27, 0, 0x18000
	v_add_u32_e32 v143, s27, v133
	s_add_i32 s29, 0, 0x1c000
	ds_read_b128 v[150:153], v143
	ds_read_b128 v[154:157], v143 offset:1024
	ds_read_b128 v[158:161], v143 offset:2048
	ds_read_b128 v[162:165], v143 offset:3072
	v_add_u32_e32 v143, s29, v133
	ds_read_b128 v[170:173], v143
	ds_read_b128 v[174:177], v143 offset:1024
	ds_read_b128 v[182:185], v143 offset:2048
	ds_read_b128 v[186:189], v143 offset:3072
	s_add_u32 s10, s10, 0xb0000
	s_addc_u32 s11, s11, 0
	s_mov_b32 m0, s22
	v_lshl_add_u64 v[232:233], s[10:11], 0, v[118:119]
	ds_read_b128 v[190:193], v142 offset:32768
	ds_read_b128 v[194:197], v142 offset:33792
	ds_read_b128 v[198:201], v142 offset:34816
	ds_read_b128 v[202:205], v142 offset:35840
	ds_read_b128 v[214:217], v142 offset:36864
	ds_read_b128 v[218:221], v142 offset:37888
	ds_read_b128 v[222:225], v142 offset:38912
	ds_read_b128 v[226:229], v142 offset:39936
	global_load_lds_dwordx4 v[232:233], off
	v_lshl_add_u64 v[232:233], s[10:11], 0, v[120:121]
	s_mov_b32 m0, s23
	s_nop 0
	global_load_lds_dwordx4 v[232:233], off
	s_waitcnt vmcnt(8)
	s_waitcnt lgkmcnt(0)
	s_barrier
	s_setprio 1
	s_waitcnt lgkmcnt(0)
	v_mfma_f32_16x16x32_bf16 v[138:141], v[150:153], v[190:193], v[138:141]
	v_mfma_f32_16x16x32_bf16 v[134:137], v[158:161], v[190:193], v[134:137]
	v_mfma_f32_16x16x32_bf16 v[110:113], v[150:153], v[198:201], v[110:113]
	v_mfma_f32_16x16x32_bf16 v[106:109], v[158:161], v[198:201], v[106:109]
	v_mfma_f32_16x16x32_bf16 v[94:97], v[150:153], v[214:217], v[94:97]
	v_mfma_f32_16x16x32_bf16 v[90:93], v[158:161], v[214:217], v[90:93]
	v_mfma_f32_16x16x32_bf16 v[78:81], v[150:153], v[222:225], v[78:81]
	v_mfma_f32_16x16x32_bf16 v[74:77], v[158:161], v[222:225], v[74:77]
	v_mfma_f32_16x16x32_bf16 v[138:141], v[154:157], v[194:197], v[138:141]
	v_mfma_f32_16x16x32_bf16 v[134:137], v[162:165], v[194:197], v[134:137]
	v_mfma_f32_16x16x32_bf16 v[110:113], v[154:157], v[202:205], v[110:113]
	v_mfma_f32_16x16x32_bf16 v[106:109], v[162:165], v[202:205], v[106:109]
	v_mfma_f32_16x16x32_bf16 v[94:97], v[154:157], v[218:221], v[94:97]
	v_mfma_f32_16x16x32_bf16 v[90:93], v[162:165], v[218:221], v[90:93]
	v_mfma_f32_16x16x32_bf16 v[78:81], v[154:157], v[226:229], v[78:81]
	v_mfma_f32_16x16x32_bf16 v[74:77], v[162:165], v[226:229], v[74:77]
	s_setprio 0
	s_setprio 1
	v_mfma_f32_16x16x32_bf16 v[122:125], v[170:173], v[190:193], v[122:125]
	v_mfma_f32_16x16x32_bf16 v[114:117], v[182:185], v[190:193], v[114:117]
	v_mfma_f32_16x16x32_bf16 v[102:105], v[170:173], v[198:201], v[102:105]
	v_mfma_f32_16x16x32_bf16 v[98:101], v[182:185], v[198:201], v[98:101]
	v_mfma_f32_16x16x32_bf16 v[86:89], v[170:173], v[214:217], v[86:89]
	v_mfma_f32_16x16x32_bf16 v[82:85], v[182:185], v[214:217], v[82:85]
	v_mfma_f32_16x16x32_bf16 v[70:73], v[170:173], v[222:225], v[70:73]
	v_mfma_f32_16x16x32_bf16 v[66:69], v[182:185], v[222:225], v[66:69]
	v_mfma_f32_16x16x32_bf16 v[122:125], v[174:177], v[194:197], v[122:125]
	v_mfma_f32_16x16x32_bf16 v[114:117], v[186:189], v[194:197], v[114:117]
	v_mfma_f32_16x16x32_bf16 v[102:105], v[174:177], v[202:205], v[102:105]
	v_mfma_f32_16x16x32_bf16 v[98:101], v[186:189], v[202:205], v[98:101]
	v_mfma_f32_16x16x32_bf16 v[86:89], v[174:177], v[218:221], v[86:89]
	v_mfma_f32_16x16x32_bf16 v[82:85], v[186:189], v[218:221], v[82:85]
	v_mfma_f32_16x16x32_bf16 v[70:73], v[174:177], v[226:229], v[70:73]
	v_mfma_f32_16x16x32_bf16 v[66:69], v[186:189], v[226:229], v[66:69]
	s_setprio 0
	s_barrier
	s_add_i32 s10, s27, s19
	v_lshl_add_u64 v[144:145], v[144:145], 0, s[14:15]
	s_mov_b32 m0, s10
	ds_read_b128 v[190:193], v142 offset:49152
	ds_read_b128 v[194:197], v142 offset:50176
	ds_read_b128 v[198:201], v142 offset:51200
	ds_read_b128 v[202:205], v142 offset:52224
	ds_read_b128 v[214:217], v142 offset:53248
	ds_read_b128 v[218:221], v142 offset:54272
	ds_read_b128 v[222:225], v142 offset:55296
	ds_read_b128 v[226:229], v142 offset:56320
	global_load_lds_dwordx4 v[144:145], off
	s_add_i32 m0, s10, 0x2000
	s_add_u32 s8, s8, 0xb0080
	v_lshl_add_u64 v[144:145], v[166:167], 0, s[14:15]
	s_addc_u32 s9, s9, 0
	s_add_i32 s10, s29, s19
	global_load_lds_dwordx4 v[144:145], off
	v_lshl_add_u64 v[144:145], s[8:9], 0, v[0:1]
	s_mov_b32 m0, s10
	s_nop 0
	global_load_lds_dwordx4 v[144:145], off
	v_lshl_add_u64 v[144:145], s[8:9], 0, v[126:127]
	s_add_i32 m0, s10, 0x2000
	s_nop 0
	global_load_lds_dwordx4 v[144:145], off
	v_lshl_add_u64 v[144:145], v[178:179], 0, s[14:15]
	s_mov_b32 m0, s24
	s_nop 0
	global_load_lds_dwordx4 v[144:145], off
	v_lshl_add_u64 v[144:145], v[230:231], 0, s[14:15]
	s_mov_b32 m0, s25
	s_nop 0
	global_load_lds_dwordx4 v[144:145], off
	s_waitcnt vmcnt(8)
	s_waitcnt lgkmcnt(0)
	s_barrier
	s_setprio 1
	s_waitcnt lgkmcnt(0)
	v_mfma_f32_16x16x32_bf16 v[62:65], v[150:153], v[190:193], v[62:65]
	v_mfma_f32_16x16x32_bf16 v[58:61], v[158:161], v[190:193], v[58:61]
	v_mfma_f32_16x16x32_bf16 v[46:49], v[150:153], v[198:201], v[46:49]
	v_mfma_f32_16x16x32_bf16 v[42:45], v[158:161], v[198:201], v[42:45]
	v_mfma_f32_16x16x32_bf16 v[30:33], v[150:153], v[214:217], v[30:33]
	v_mfma_f32_16x16x32_bf16 v[26:29], v[158:161], v[214:217], v[26:29]
	v_mfma_f32_16x16x32_bf16 v[14:17], v[150:153], v[222:225], v[14:17]
	v_mfma_f32_16x16x32_bf16 v[10:13], v[158:161], v[222:225], v[10:13]
	v_mfma_f32_16x16x32_bf16 v[62:65], v[154:157], v[194:197], v[62:65]
	v_mfma_f32_16x16x32_bf16 v[58:61], v[162:165], v[194:197], v[58:61]
	v_mfma_f32_16x16x32_bf16 v[46:49], v[154:157], v[202:205], v[46:49]
	v_mfma_f32_16x16x32_bf16 v[42:45], v[162:165], v[202:205], v[42:45]
	v_mfma_f32_16x16x32_bf16 v[30:33], v[154:157], v[218:221], v[30:33]
	v_mfma_f32_16x16x32_bf16 v[26:29], v[162:165], v[218:221], v[26:29]
	v_mfma_f32_16x16x32_bf16 v[14:17], v[154:157], v[226:229], v[14:17]
	v_mfma_f32_16x16x32_bf16 v[10:13], v[162:165], v[226:229], v[10:13]
	s_setprio 0
	s_setprio 1
	v_mfma_f32_16x16x32_bf16 v[54:57], v[170:173], v[190:193], v[54:57]
	v_mfma_f32_16x16x32_bf16 v[50:53], v[182:185], v[190:193], v[50:53]
	v_mfma_f32_16x16x32_bf16 v[38:41], v[170:173], v[198:201], v[38:41]
	v_mfma_f32_16x16x32_bf16 v[34:37], v[182:185], v[198:201], v[34:37]
	v_mfma_f32_16x16x32_bf16 v[22:25], v[170:173], v[214:217], v[22:25]
	v_mfma_f32_16x16x32_bf16 v[18:21], v[182:185], v[214:217], v[18:21]
	v_mfma_f32_16x16x32_bf16 v[6:9], v[170:173], v[222:225], v[6:9]
	v_mfma_f32_16x16x32_bf16 v[2:5], v[182:185], v[222:225], v[2:5]
	v_mfma_f32_16x16x32_bf16 v[54:57], v[174:177], v[194:197], v[54:57]
	v_mfma_f32_16x16x32_bf16 v[50:53], v[186:189], v[194:197], v[50:53]
	v_mfma_f32_16x16x32_bf16 v[38:41], v[174:177], v[202:205], v[38:41]
	v_mfma_f32_16x16x32_bf16 v[34:37], v[186:189], v[202:205], v[34:37]
	v_mfma_f32_16x16x32_bf16 v[22:25], v[174:177], v[218:221], v[22:25]
	v_mfma_f32_16x16x32_bf16 v[18:21], v[186:189], v[218:221], v[18:21]
	v_mfma_f32_16x16x32_bf16 v[6:9], v[174:177], v[226:229], v[6:9]
	v_mfma_f32_16x16x32_bf16 v[2:5], v[186:189], v[226:229], v[2:5]
	s_setprio 0
	s_barrier
	s_add_i32 s26, s26, 2
	s_add_u32 s6, s6, 0x100
	s_addc_u32 s7, s7, 0
	s_cmp_gt_u32 s26, 41
	s_cbranch_scc1 .Lpeel_k1382_exit

.Lpeel_k1382_exit:
	s_cmpk_lt_u32 s18, 0x100
	s_cbranch_scc0 .LBB0_1385
	s_barrier

.LBB0_1545:
	s_ashr_i32 s41, s40, 31
	s_lshl_b64 s[42:43], s[40:41], 19
	s_add_u32 s42, s13, s42
	s_addc_u32 s43, s16, s43
	s_and_b64 s[44:45], s[36:37], exec
	s_cselect_b32 s5, s43, s47
	s_cselect_b32 s41, s42, s46
	s_ashr_i32 s39, s38, 31
	s_lshl_b64 s[44:45], s[38:39], 19
	s_add_u32 s44, s20, s44
	s_addc_u32 s45, s21, s45
	s_and_b64 s[50:51], s[36:37], exec
	s_cselect_b32 s39, s45, s49
	s_cselect_b32 s57, s44, s48
	s_add_u32 s46, s46, 0x40080
	s_addc_u32 s47, s47, 0
	s_add_u32 s58, s48, 0x100
	v_mov_b32_e32 v2, 0
	s_addc_u32 s59, s49, 0
	s_mov_b32 s60, -2
	s_add_u32 s48, s46, 0xfffc0080
	s_addc_u32 s49, s47, -1
	s_add_i32 s61, 0, 0x10000
	s_cmp_eq_u32 s60, 12
	s_cselect_b32 s51, s5, s49
	s_cselect_b32 s50, s41, s48
	s_cselect_b32 s49, s39, s59
	s_cselect_b32 s48, s57, s58
	s_add_i32 s64, 0, 0x14000
	v_add_u32_e32 v126, s61, v165
	v_add_u32_e32 v164, s64, v165
	ds_read_b128 v[106:109], v126
	ds_read_b128 v[114:117], v126 offset:1024
	ds_read_b128 v[122:125], v126 offset:2048
	ds_read_b128 v[126:129], v126 offset:3072
	ds_read_b128 v[178:181], v164
	ds_read_b128 v[188:191], v164 offset:1024
	ds_read_b128 v[192:195], v164 offset:2048
	ds_read_b128 v[196:199], v164 offset:3072
	v_lshl_add_u64 v[166:167], s[46:47], 0, v[160:161]
	s_add_i32 m0, s27, 0xc000
	ds_read_b128 v[200:203], v171
	ds_read_b128 v[214:217], v171 offset:1024
	ds_read_b128 v[218:221], v171 offset:2048
	ds_read_b128 v[222:225], v171 offset:3072
	ds_read_b128 v[226:229], v171 offset:4096
	ds_read_b128 v[230:233], v171 offset:5120
	ds_read_b128 v[234:237], v171 offset:6144
	ds_read_b128 v[238:241], v171 offset:7168
	global_load_lds_dwordx4 v[166:167], off
	v_lshl_add_u64 v[166:167], s[46:47], 0, v[162:163]
	s_add_i32 m0, s27, 0xe000
	s_nop 0
	global_load_lds_dwordx4 v[166:167], off
	s_waitcnt vmcnt(8)
	s_waitcnt lgkmcnt(0)
	s_barrier
	s_setprio 1
	s_waitcnt lgkmcnt(0)
	v_mfma_f32_16x16x32_bf16 v[142:145], v[106:109], v[200:203], 0
	v_mfma_f32_16x16x32_bf16 v[138:141], v[122:125], v[200:203], 0
	v_mfma_f32_16x16x32_bf16 v[118:121], v[106:109], v[218:221], 0
	v_mfma_f32_16x16x32_bf16 v[110:113], v[122:125], v[218:221], 0
	v_mfma_f32_16x16x32_bf16 v[94:97], v[106:109], v[226:229], 0
	v_mfma_f32_16x16x32_bf16 v[90:93], v[122:125], v[226:229], 0
	v_mfma_f32_16x16x32_bf16 v[78:81], v[106:109], v[234:237], 0
	v_mfma_f32_16x16x32_bf16 v[74:77], v[122:125], v[234:237], 0
	v_mfma_f32_16x16x32_bf16 v[142:145], v[114:117], v[214:217], v[142:145]
	v_mfma_f32_16x16x32_bf16 v[138:141], v[126:129], v[214:217], v[138:141]
	v_mfma_f32_16x16x32_bf16 v[118:121], v[114:117], v[222:225], v[118:121]
	v_mfma_f32_16x16x32_bf16 v[110:113], v[126:129], v[222:225], v[110:113]
	v_mfma_f32_16x16x32_bf16 v[94:97], v[114:117], v[230:233], v[94:97]
	v_mfma_f32_16x16x32_bf16 v[90:93], v[126:129], v[230:233], v[90:93]
	v_mfma_f32_16x16x32_bf16 v[78:81], v[114:117], v[238:241], v[78:81]
	v_mfma_f32_16x16x32_bf16 v[74:77], v[126:129], v[238:241], v[74:77]
	s_setprio 0
	s_setprio 1
	v_mfma_f32_16x16x32_bf16 v[134:137], v[178:181], v[200:203], 0
	v_mfma_f32_16x16x32_bf16 v[130:133], v[192:195], v[200:203], 0
	v_mfma_f32_16x16x32_bf16 v[102:105], v[178:181], v[218:221], 0
	v_mfma_f32_16x16x32_bf16 v[98:101], v[192:195], v[218:221], 0
	v_mfma_f32_16x16x32_bf16 v[86:89], v[178:181], v[226:229], 0
	v_mfma_f32_16x16x32_bf16 v[82:85], v[192:195], v[226:229], 0
	v_mfma_f32_16x16x32_bf16 v[70:73], v[178:181], v[234:237], 0
	v_mfma_f32_16x16x32_bf16 v[66:69], v[192:195], v[234:237], 0
	v_mfma_f32_16x16x32_bf16 v[134:137], v[188:191], v[214:217], v[134:137]
	v_mfma_f32_16x16x32_bf16 v[130:133], v[196:199], v[214:217], v[130:133]
	v_mfma_f32_16x16x32_bf16 v[102:105], v[188:191], v[222:225], v[102:105]
	v_mfma_f32_16x16x32_bf16 v[98:101], v[196:199], v[222:225], v[98:101]
	v_mfma_f32_16x16x32_bf16 v[86:89], v[188:191], v[230:233], v[86:89]
	v_mfma_f32_16x16x32_bf16 v[82:85], v[196:199], v[230:233], v[82:85]
	v_mfma_f32_16x16x32_bf16 v[70:73], v[188:191], v[238:241], v[70:73]
	v_mfma_f32_16x16x32_bf16 v[66:69], v[196:199], v[238:241], v[66:69]
	s_setprio 0
	s_barrier
	s_add_i32 s61, s61, s26
	v_lshl_add_u64 v[166:167], s[48:49], 0, v[0:1]
	s_mov_b32 m0, s61
	ds_read_b128 v[200:203], v171 offset:16384
	ds_read_b128 v[214:217], v171 offset:17408
	ds_read_b128 v[218:221], v171 offset:18432
	ds_read_b128 v[222:225], v171 offset:19456
	ds_read_b128 v[226:229], v171 offset:20480
	ds_read_b128 v[230:233], v171 offset:21504
	ds_read_b128 v[234:237], v171 offset:22528
	ds_read_b128 v[238:241], v171 offset:23552
	global_load_lds_dwordx4 v[166:167], off
	s_add_i32 m0, s61, 0x2000
	s_add_u32 s62, s48, 0x40000
	v_lshl_add_u64 v[174:175], s[48:49], 0, v[154:155]
	s_addc_u32 s63, s49, 0
	s_add_i32 s61, s64, s26
	global_load_lds_dwordx4 v[174:175], off
	v_lshl_add_u64 v[184:185], s[62:63], 0, v[0:1]
	s_mov_b32 m0, s61
	v_lshl_add_u64 v[204:205], s[50:51], 0, v[152:153]
	global_load_lds_dwordx4 v[184:185], off
	v_lshl_add_u64 v[184:185], s[62:63], 0, v[154:155]
	s_add_i32 m0, s61, 0x2000
	s_nop 0
	global_load_lds_dwordx4 v[184:185], off
	v_lshl_add_u64 v[184:185], s[50:51], 0, v[150:151]
	s_mov_b32 m0, s27
	s_nop 0
	global_load_lds_dwordx4 v[184:185], off
	s_mov_b32 m0, s34
	s_nop 0
	global_load_lds_dwordx4 v[204:205], off
	s_waitcnt vmcnt(8)
	s_waitcnt lgkmcnt(0)
	s_barrier
	s_setprio 1
	s_waitcnt lgkmcnt(0)
	v_mfma_f32_16x16x32_bf16 v[62:65], v[106:109], v[200:203], 0
	v_mfma_f32_16x16x32_bf16 v[58:61], v[122:125], v[200:203], 0
	v_mfma_f32_16x16x32_bf16 v[46:49], v[106:109], v[218:221], 0
	v_mfma_f32_16x16x32_bf16 v[42:45], v[122:125], v[218:221], 0
	v_mfma_f32_16x16x32_bf16 v[30:33], v[106:109], v[226:229], 0
	v_mfma_f32_16x16x32_bf16 v[26:29], v[122:125], v[226:229], 0
	v_mfma_f32_16x16x32_bf16 v[14:17], v[106:109], v[234:237], 0
	v_mfma_f32_16x16x32_bf16 v[10:13], v[122:125], v[234:237], 0
	v_mfma_f32_16x16x32_bf16 v[62:65], v[114:117], v[214:217], v[62:65]
	v_mfma_f32_16x16x32_bf16 v[58:61], v[126:129], v[214:217], v[58:61]
	v_mfma_f32_16x16x32_bf16 v[46:49], v[114:117], v[222:225], v[46:49]
	v_mfma_f32_16x16x32_bf16 v[42:45], v[126:129], v[222:225], v[42:45]
	v_mfma_f32_16x16x32_bf16 v[30:33], v[114:117], v[230:233], v[30:33]
	v_mfma_f32_16x16x32_bf16 v[26:29], v[126:129], v[230:233], v[26:29]
	v_mfma_f32_16x16x32_bf16 v[14:17], v[114:117], v[238:241], v[14:17]
	v_mfma_f32_16x16x32_bf16 v[10:13], v[126:129], v[238:241], v[10:13]
	s_setprio 0
	s_setprio 1
	v_mfma_f32_16x16x32_bf16 v[54:57], v[178:181], v[200:203], 0
	v_mfma_f32_16x16x32_bf16 v[50:53], v[192:195], v[200:203], 0
	v_mfma_f32_16x16x32_bf16 v[38:41], v[178:181], v[218:221], 0
	v_mfma_f32_16x16x32_bf16 v[34:37], v[192:195], v[218:221], 0
	v_mfma_f32_16x16x32_bf16 v[22:25], v[178:181], v[226:229], 0
	v_mfma_f32_16x16x32_bf16 v[18:21], v[192:195], v[226:229], 0
	v_mfma_f32_16x16x32_bf16 v[6:9], v[178:181], v[234:237], 0
	v_mfma_f32_16x16x32_bf16 v[2:5], v[192:195], v[234:237], 0
	v_mfma_f32_16x16x32_bf16 v[54:57], v[188:191], v[214:217], v[54:57]
	v_mfma_f32_16x16x32_bf16 v[50:53], v[196:199], v[214:217], v[50:53]
	v_mfma_f32_16x16x32_bf16 v[38:41], v[188:191], v[222:225], v[38:41]
	v_mfma_f32_16x16x32_bf16 v[34:37], v[196:199], v[222:225], v[34:37]
	v_mfma_f32_16x16x32_bf16 v[22:25], v[188:191], v[230:233], v[22:25]
	v_mfma_f32_16x16x32_bf16 v[18:21], v[196:199], v[230:233], v[18:21]
	v_mfma_f32_16x16x32_bf16 v[6:9], v[188:191], v[238:241], v[6:9]
	v_mfma_f32_16x16x32_bf16 v[2:5], v[196:199], v[238:241], v[2:5]
	s_setprio 0
	s_barrier
	s_add_i32 s61, 0, 0x18000
	s_add_i32 s62, 0, 0x1c000
	v_add_u32_e32 v126, s61, v165
	v_add_u32_e32 v164, s62, v165
	ds_read_b128 v[106:109], v126
	ds_read_b128 v[114:117], v126 offset:1024
	ds_read_b128 v[122:125], v126 offset:2048
	ds_read_b128 v[126:129], v126 offset:3072
	ds_read_b128 v[178:181], v164
	ds_read_b128 v[188:191], v164 offset:1024
	ds_read_b128 v[192:195], v164 offset:2048
	ds_read_b128 v[196:199], v164 offset:3072
	s_add_u32 s50, s50, 0x40000
	s_addc_u32 s51, s51, 0
	s_mov_b32 m0, s52
	v_lshl_add_u64 v[242:243], s[50:51], 0, v[150:151]
	ds_read_b128 v[200:203], v171 offset:32768
	ds_read_b128 v[214:217], v171 offset:33792
	ds_read_b128 v[218:221], v171 offset:34816
	ds_read_b128 v[222:225], v171 offset:35840
	ds_read_b128 v[226:229], v171 offset:36864
	ds_read_b128 v[230:233], v171 offset:37888
	ds_read_b128 v[234:237], v171 offset:38912
	ds_read_b128 v[238:241], v171 offset:39936
	global_load_lds_dwordx4 v[242:243], off
	v_lshl_add_u64 v[242:243], s[50:51], 0, v[152:153]
	s_mov_b32 m0, s53
	s_nop 0
	global_load_lds_dwordx4 v[242:243], off
	s_waitcnt vmcnt(8)
	s_waitcnt lgkmcnt(0)
	s_barrier
	s_setprio 1
	s_waitcnt lgkmcnt(0)
	v_mfma_f32_16x16x32_bf16 v[142:145], v[106:109], v[200:203], v[142:145]
	v_mfma_f32_16x16x32_bf16 v[138:141], v[122:125], v[200:203], v[138:141]
	v_mfma_f32_16x16x32_bf16 v[118:121], v[106:109], v[218:221], v[118:121]
	v_mfma_f32_16x16x32_bf16 v[110:113], v[122:125], v[218:221], v[110:113]
	v_mfma_f32_16x16x32_bf16 v[94:97], v[106:109], v[226:229], v[94:97]
	v_mfma_f32_16x16x32_bf16 v[90:93], v[122:125], v[226:229], v[90:93]
	v_mfma_f32_16x16x32_bf16 v[78:81], v[106:109], v[234:237], v[78:81]
	v_mfma_f32_16x16x32_bf16 v[74:77], v[122:125], v[234:237], v[74:77]
	v_mfma_f32_16x16x32_bf16 v[142:145], v[114:117], v[214:217], v[142:145]
	v_mfma_f32_16x16x32_bf16 v[138:141], v[126:129], v[214:217], v[138:141]
	v_mfma_f32_16x16x32_bf16 v[118:121], v[114:117], v[222:225], v[118:121]
	v_mfma_f32_16x16x32_bf16 v[110:113], v[126:129], v[222:225], v[110:113]
	v_mfma_f32_16x16x32_bf16 v[94:97], v[114:117], v[230:233], v[94:97]
	v_mfma_f32_16x16x32_bf16 v[90:93], v[126:129], v[230:233], v[90:93]
	v_mfma_f32_16x16x32_bf16 v[78:81], v[114:117], v[238:241], v[78:81]
	v_mfma_f32_16x16x32_bf16 v[74:77], v[126:129], v[238:241], v[74:77]
	s_setprio 0
	s_setprio 1
	v_mfma_f32_16x16x32_bf16 v[134:137], v[178:181], v[200:203], v[134:137]
	v_mfma_f32_16x16x32_bf16 v[130:133], v[192:195], v[200:203], v[130:133]
	v_mfma_f32_16x16x32_bf16 v[102:105], v[178:181], v[218:221], v[102:105]
	v_mfma_f32_16x16x32_bf16 v[98:101], v[192:195], v[218:221], v[98:101]
	v_mfma_f32_16x16x32_bf16 v[86:89], v[178:181], v[226:229], v[86:89]
	v_mfma_f32_16x16x32_bf16 v[82:85], v[192:195], v[226:229], v[82:85]
	v_mfma_f32_16x16x32_bf16 v[70:73], v[178:181], v[234:237], v[70:73]
	v_mfma_f32_16x16x32_bf16 v[66:69], v[192:195], v[234:237], v[66:69]
	v_mfma_f32_16x16x32_bf16 v[134:137], v[188:191], v[214:217], v[134:137]
	v_mfma_f32_16x16x32_bf16 v[130:133], v[196:199], v[214:217], v[130:133]
	v_mfma_f32_16x16x32_bf16 v[102:105], v[188:191], v[222:225], v[102:105]
	v_mfma_f32_16x16x32_bf16 v[98:101], v[196:199], v[222:225], v[98:101]
	v_mfma_f32_16x16x32_bf16 v[86:89], v[188:191], v[230:233], v[86:89]
	v_mfma_f32_16x16x32_bf16 v[82:85], v[196:199], v[230:233], v[82:85]
	v_mfma_f32_16x16x32_bf16 v[70:73], v[188:191], v[238:241], v[70:73]
	v_mfma_f32_16x16x32_bf16 v[66:69], v[196:199], v[238:241], v[66:69]
	s_setprio 0
	s_barrier
	s_add_i32 s50, s61, s26
	v_lshl_add_u64 v[166:167], v[166:167], 0, s[14:15]
	s_mov_b32 m0, s50
	ds_read_b128 v[200:203], v171 offset:49152
	ds_read_b128 v[214:217], v171 offset:50176
	ds_read_b128 v[218:221], v171 offset:51200
	ds_read_b128 v[222:225], v171 offset:52224
	ds_read_b128 v[226:229], v171 offset:53248
	ds_read_b128 v[230:233], v171 offset:54272
	ds_read_b128 v[234:237], v171 offset:55296
	ds_read_b128 v[238:241], v171 offset:56320
	global_load_lds_dwordx4 v[166:167], off
	s_add_i32 m0, s50, 0x2000
	s_add_u32 s48, s48, 0x40080
	v_lshl_add_u64 v[166:167], v[174:175], 0, s[14:15]
	s_addc_u32 s49, s49, 0
	s_add_i32 s50, s62, s26
	global_load_lds_dwordx4 v[166:167], off
	v_lshl_add_u64 v[166:167], s[48:49], 0, v[0:1]
	s_mov_b32 m0, s50
	s_nop 0
	global_load_lds_dwordx4 v[166:167], off
	v_lshl_add_u64 v[166:167], s[48:49], 0, v[154:155]
	s_add_i32 m0, s50, 0x2000
	s_nop 0
	global_load_lds_dwordx4 v[166:167], off
	v_lshl_add_u64 v[166:167], v[184:185], 0, s[14:15]
	s_mov_b32 m0, s54
	s_nop 0
	global_load_lds_dwordx4 v[166:167], off
	v_lshl_add_u64 v[166:167], v[204:205], 0, s[14:15]
	s_mov_b32 m0, s55
	s_nop 0
	global_load_lds_dwordx4 v[166:167], off
	s_waitcnt vmcnt(8)
	s_waitcnt lgkmcnt(0)
	s_barrier
	s_setprio 1
	s_waitcnt lgkmcnt(0)
	v_mfma_f32_16x16x32_bf16 v[62:65], v[106:109], v[200:203], v[62:65]
	v_mfma_f32_16x16x32_bf16 v[58:61], v[122:125], v[200:203], v[58:61]
	v_mfma_f32_16x16x32_bf16 v[46:49], v[106:109], v[218:221], v[46:49]
	v_mfma_f32_16x16x32_bf16 v[42:45], v[122:125], v[218:221], v[42:45]
	v_mfma_f32_16x16x32_bf16 v[30:33], v[106:109], v[226:229], v[30:33]
	v_mfma_f32_16x16x32_bf16 v[26:29], v[122:125], v[226:229], v[26:29]
	v_mfma_f32_16x16x32_bf16 v[14:17], v[106:109], v[234:237], v[14:17]
	v_mfma_f32_16x16x32_bf16 v[10:13], v[122:125], v[234:237], v[10:13]
	v_mfma_f32_16x16x32_bf16 v[62:65], v[114:117], v[214:217], v[62:65]
	v_mfma_f32_16x16x32_bf16 v[58:61], v[126:129], v[214:217], v[58:61]
	v_mfma_f32_16x16x32_bf16 v[46:49], v[114:117], v[222:225], v[46:49]
	v_mfma_f32_16x16x32_bf16 v[42:45], v[126:129], v[222:225], v[42:45]
	v_mfma_f32_16x16x32_bf16 v[30:33], v[114:117], v[230:233], v[30:33]
	v_mfma_f32_16x16x32_bf16 v[26:29], v[126:129], v[230:233], v[26:29]
	v_mfma_f32_16x16x32_bf16 v[14:17], v[114:117], v[238:241], v[14:17]
	v_mfma_f32_16x16x32_bf16 v[10:13], v[126:129], v[238:241], v[10:13]
	s_setprio 0
	s_setprio 1
	v_mfma_f32_16x16x32_bf16 v[54:57], v[178:181], v[200:203], v[54:57]
	v_mfma_f32_16x16x32_bf16 v[50:53], v[192:195], v[200:203], v[50:53]
	v_mfma_f32_16x16x32_bf16 v[38:41], v[178:181], v[218:221], v[38:41]
	v_mfma_f32_16x16x32_bf16 v[34:37], v[192:195], v[218:221], v[34:37]
	v_mfma_f32_16x16x32_bf16 v[22:25], v[178:181], v[226:229], v[22:25]
	v_mfma_f32_16x16x32_bf16 v[18:21], v[192:195], v[226:229], v[18:21]
	v_mfma_f32_16x16x32_bf16 v[6:9], v[178:181], v[234:237], v[6:9]
	v_mfma_f32_16x16x32_bf16 v[2:5], v[192:195], v[234:237], v[2:5]
	v_mfma_f32_16x16x32_bf16 v[54:57], v[188:191], v[214:217], v[54:57]
	v_mfma_f32_16x16x32_bf16 v[50:53], v[196:199], v[214:217], v[50:53]
	v_mfma_f32_16x16x32_bf16 v[38:41], v[188:191], v[222:225], v[38:41]
	v_mfma_f32_16x16x32_bf16 v[34:37], v[196:199], v[222:225], v[34:37]
	v_mfma_f32_16x16x32_bf16 v[22:25], v[188:191], v[230:233], v[22:25]
	v_mfma_f32_16x16x32_bf16 v[18:21], v[196:199], v[230:233], v[18:21]
	v_mfma_f32_16x16x32_bf16 v[6:9], v[188:191], v[238:241], v[6:9]
	v_mfma_f32_16x16x32_bf16 v[2:5], v[196:199], v[238:241], v[2:5]
	s_setprio 0
	s_barrier
	s_add_i32 s60, s60, 2
	s_add_u32 s46, s46, 0x100
	s_addc_u32 s47, s47, 0
	s_add_u32 s58, s58, 0x100
	s_addc_u32 s59, s59, 0
	s_cmp_gt_u32 s60, 13
	s_cbranch_scc1 .Lpeel_k1546_exit

.Lpeel_k1546_exit:
	s_and_b64 vcc, exec, s[30:31]
	s_cbranch_vccz .LBB0_1549
	s_barrier
